# mLSTM: next-chunk prefetch (K LDS-DMA, q frags, v) of waves 0-3 issued after barrier 1 instead of in the serial W segment, prefetch waits moved to the loop latch, counted lgkmcnt in QK^T / qC^T pipeli
# speedup vs baseline: 1.0220x; 1.0137x over previous
; __global__ void __launch_bounds__(512, 2) mega(Params Pk) {
;     ...
;         if (threadIdx.x == 0) { unsigned* mc = (unsigned*)S7(BAR_OFF) + 3584; unsigned sp_ = 0;
;             while (__hip_atomic_load(mc, __ATOMIC_RELAXED, __HIP_MEMORY_SCOPE_AGENT) < 64u) { __builtin_amdgcn_s_sleep(1); if (++sp_ > (1u << 22)) { atomicAdd((unsigned*)S7(BAR_OFF) + XB_TMO, 1u); break; } }
;             __builtin_amdgcn_fence(__ATOMIC_ACQUIRE, "agent"); asm volatile("s_waitcnt vmcnt(0)" ::: "memory"); }
.LBB0_26:
	s_nop 0
	global_load_dword v0, v1, s[4:5] sc1
	s_mov_b64 s[6:7], -1
	s_mov_b64 s[8:9], -1
	s_waitcnt vmcnt(0)
	v_cmp_lt_u32_e32 vcc, 63, v0
	s_cbranch_vccnz .LBB0_25
	s_sleep 3
	global_load_dword v0, v1, s[4:5] sc1
	s_waitcnt vmcnt(0)
	v_cmp_gt_u32_e32 vcc, 64, v0
	s_cbranch_vccz .LBB0_25
	s_sleep 3
	global_load_dword v0, v1, s[4:5] sc1
	s_waitcnt vmcnt(0)
	v_cmp_gt_u32_e32 vcc, 64, v0
	s_cbranch_vccz .LBB0_25
	s_sleep 3
	global_load_dword v0, v1, s[4:5] sc1
	s_waitcnt vmcnt(0)
	v_cmp_gt_u32_e32 vcc, 64, v0
	s_cbranch_vccz .LBB0_25
	s_sleep 3
	global_load_dword v0, v1, s[4:5] sc1
	s_waitcnt vmcnt(0)
	v_cmp_gt_u32_e32 vcc, 64, v0
	s_cbranch_vccz .LBB0_25
	s_add_i32 s2, s2, -5
	s_cmp_eq_u32 s2, 0
	s_mov_b64 s[6:7], 0
	s_cselect_b64 s[8:9], -1, 0
	s_sleep 3
	s_branch .LBB0_25

; DEV unsigned xb_ld(unsigned* p) { return __hip_atomic_load(p, __ATOMIC_RELAXED, __HIP_MEMORY_SCOPE_AGENT); }
; DEV void xcd_barrier_complete(unsigned* bar, unsigned x, unsigned& nloc, unsigned& nx) {
;     const unsigned G = gridDim.x * gridDim.y * gridDim.z;
;     unsigned sum, cnt, mine, sp = 0u;
;     for (;;) {
;         sum = 0u; cnt = 0u; mine = 0u;
; #pragma nounroll
;         for (unsigned h = 0; h < 2; ++h) {
;             unsigned cv[8];
; #pragma unroll
;             for (unsigned j = 0; j < 8; ++j) cv[j] = xb_ld(&bar[XB_XCNT(8u * h + j)]);
; #pragma unroll
;             for (unsigned j = 0; j < 8; ++j) { sum += cv[j]; cnt += (cv[j] > 0u) ? 1u : 0u; if (8u * h + j == x) mine = cv[j]; }
;         }
;         if (sum == G) break;
;         __builtin_amdgcn_s_sleep(1);
;         if ((++sp & 255u) == 0u) { if (xb_ld(&bar[XB_TMO])) break; if (sp > XB_SPIN_CAP) { atomicAdd(&bar[XB_TMO], 1u); break; } }
;     }
;     nloc = mine > 0u ? mine : 1u; nx = cnt > 0u ? cnt : 1u;
.LBB0_45:
	s_lshl_b32 s10, s15, 9
	s_lshl_b64 s[0:1], s[10:11], 2
	s_add_u32 s0, s48, s0
	s_addc_u32 s1, s49, s1
	global_load_dword v0, v2, s[0:1] offset:1024 sc1
	global_load_dword v1, v2, s[0:1] offset:1280 sc1
	global_load_dword v6, v2, s[0:1] offset:1536 sc1
	global_load_dword v7, v2, s[0:1] offset:1792 sc1
	global_load_dword v8, v2, s[0:1] offset:2048 sc1
	global_load_dword v9, v2, s[0:1] offset:2304 sc1
	global_load_dword v10, v2, s[0:1] offset:2560 sc1
	global_load_dword v11, v2, s[0:1] offset:2816 sc1
	s_lshl_b32 s10, s15, 3
	s_cmp_eq_u32 s10, s33
	s_cselect_b64 vcc, -1, 0
	s_or_b32 s0, s10, 1
	s_cmp_eq_u32 s0, s33
	s_mov_b32 s15, 1
	s_waitcnt vmcnt(7)
	v_cmp_ne_u32_e64 s[0:1], 0, v0
	v_add_u32_e32 v5, v0, v5
	s_nop 0
	v_cndmask_b32_e64 v12, 0, 1, s[0:1]
	v_cndmask_b32_e32 v0, v4, v0, vcc
	s_waitcnt vmcnt(6)
	v_cmp_ne_u32_e32 vcc, 0, v1
	s_cselect_b64 s[0:1], -1, 0
	s_or_b32 s16, s10, 2
	s_waitcnt vmcnt(5)
	v_cmp_ne_u32_e64 s[4:5], 0, v6
	v_addc_co_u32_e32 v3, vcc, v3, v12, vcc
	s_cmp_eq_u32 s16, s33
	v_cndmask_b32_e64 v4, 0, 1, s[4:5]
	v_cndmask_b32_e64 v0, v0, v1, s[0:1]
	s_waitcnt vmcnt(4)
	v_cmp_ne_u32_e32 vcc, 0, v7
	s_cselect_b64 s[0:1], -1, 0
	s_waitcnt vmcnt(3)
	v_cmp_ne_u32_e64 s[4:5], 0, v8
	v_cndmask_b32_e64 v0, v0, v6, s[0:1]
	v_addc_co_u32_e32 v3, vcc, v3, v4, vcc
	s_or_b32 s0, s10, 3
	v_cndmask_b32_e64 v13, 0, 1, s[4:5]
	s_waitcnt vmcnt(2)
	v_cmp_ne_u32_e32 vcc, 0, v9
	s_cmp_eq_u32 s0, s33
	s_waitcnt vmcnt(1)
	v_cmp_ne_u32_e64 s[4:5], 0, v10
	v_addc_co_u32_e32 v3, vcc, v3, v13, vcc
	s_cselect_b64 s[0:1], -1, 0
	v_cndmask_b32_e64 v14, 0, 1, s[4:5]
	s_waitcnt vmcnt(0)
	v_cmp_ne_u32_e32 vcc, 0, v11
	v_cndmask_b32_e64 v0, v0, v7, s[0:1]
	s_or_b32 s0, s10, 4
	v_addc_co_u32_e32 v3, vcc, v3, v14, vcc
	s_cmp_eq_u32 s0, s33
	s_cselect_b64 vcc, -1, 0
	s_or_b32 s0, s10, 5
	v_add_u32_e32 v5, v5, v1
	s_cmp_eq_u32 s0, s33
	v_add_u32_e32 v1, v5, v6
	v_cndmask_b32_e32 v0, v0, v8, vcc
	s_cselect_b64 vcc, -1, 0
	s_or_b32 s0, s10, 6
	v_add_u32_e32 v1, v1, v7
	s_cmp_eq_u32 s0, s33
	v_add_u32_e32 v1, v1, v8
	v_cndmask_b32_e32 v0, v0, v9, vcc
	s_cselect_b64 vcc, -1, 0
	s_or_b32 s0, s10, 7
	v_add_u32_e32 v1, v1, v9
	s_cmp_eq_u32 s0, s33
	v_add_u32_e32 v1, v1, v10
	v_cndmask_b32_e32 v0, v0, v10, vcc
	s_cselect_b64 vcc, -1, 0
	v_add_u32_e32 v5, v1, v11
	v_cndmask_b32_e32 v4, v0, v11, vcc
	s_and_b64 vcc, exec, s[12:13]
	s_mov_b64 s[12:13], 0
	s_cbranch_vccnz .LBB0_45
	v_cmp_eq_u32_e32 vcc, s2, v5
	s_mov_b64 s[0:1], -1
	s_mov_b64 s[4:5], -1
	s_cbranch_vccnz .LBB0_43
	s_add_i32 s14, s14, 1
	s_and_b32 s4, s14, 0xff
	s_cmp_eq_u32 s4, 0
	s_cselect_b64 s[4:5], -1, 0
	s_and_b64 vcc, exec, s[4:5]
	s_sleep 3
	s_cbranch_vccz .LBB0_43
	global_load_dword v0, v2, s[8:9] sc1
	s_waitcnt vmcnt(0)
	v_cmp_eq_u32_e32 vcc, 0, v0
	s_cbranch_vccz .LBB0_43
	s_cmp_gt_u32 s14, 0x40000
	s_mov_b64 s[0:1], 0
	s_cselect_b64 s[4:5], -1, 0
	s_branch .LBB0_43

; DEV int opaque_tid() { int t = threadIdx.x; asm volatile("" : "+v"(t)); return t; }
; #define LAS __attribute__((address_space(3)))
; DEV unsigned xb_ld(unsigned* p) { return __hip_atomic_load(p, __ATOMIC_RELAXED, __HIP_MEMORY_SCOPE_AGENT); }
; DEV unsigned xb_add(unsigned* p, unsigned v) { return __hip_atomic_fetch_add(p, v, __ATOMIC_RELAXED, __HIP_MEMORY_SCOPE_AGENT); }
; DEV unsigned xb_xcc_id() { return (unsigned)__builtin_amdgcn_s_getreg((3 << 11) | 20) & 0xFu; }
; #define XB_SPIN(cond, bar) do { unsigned _sp = 0; while (cond) { __builtin_amdgcn_s_sleep(1); \
;     if ((++_sp & 255u) == 0u) { if (xb_ld(&(bar)[XB_TMO])) break; if (_sp > XB_SPIN_CAP) { atomicAdd(&(bar)[XB_TMO], 1u); break; } } } } while (0)
; DEV void xcd_wait_lds(LAS char* lds) {
;     volatile LAS unsigned* st = (volatile LAS unsigned*)(lds + LDS_BYTES - 16);
;     const int tid_ = opaque_tid();
;     if (tid_ == 64) asm volatile("buffer_inv sc1\n\ts_waitcnt vmcnt(0)" ::: "memory");
;     if (tid_ == 0) {
;         unsigned* bar = (unsigned*)((char*)ldptr(lds, 30) + SLOTS * 7 + BAR_OFF);
;         const unsigned x = xb_xcc_id();
;         const unsigned mode = st[2], val = st[3];
;         if (mode != 3u) XB_SPIN(xb_ld(&bar[XB_TOPGEN]) <= val, bar);
;         if (mode == 2u) xb_add(&bar[XB_XGEN(x)], 1u);
;         asm volatile("s_waitcnt vmcnt(0)" ::: "memory");
;     }
;     asm volatile("s_waitcnt lgkmcnt(0)\n\ts_barrier" ::: "memory");
;     if (tid_ == 0) st[2] = 0u;
.LBB0_185:
	s_and_b32 s14, s18, 0xff
	s_mov_b64 s[12:13], -1
	s_cmp_lg_u32 s14, 0
	s_mov_b64 s[16:17], -1
	s_sleep 3
	s_cbranch_scc0 .LBB0_188
	s_and_b64 vcc, exec, s[16:17]
	s_cbranch_vccz .LBB0_184

; DEV unsigned xb_ld(unsigned* p) { return __hip_atomic_load(p, __ATOMIC_RELAXED, __HIP_MEMORY_SCOPE_AGENT); }
; DEV void xcd_barrier_complete(unsigned* bar, unsigned x, unsigned& nloc, unsigned& nx) {
;     const unsigned G = gridDim.x * gridDim.y * gridDim.z;
;     unsigned sum, cnt, mine, sp = 0u;
;     for (;;) {
;         sum = 0u; cnt = 0u; mine = 0u;
; #pragma nounroll
;         for (unsigned h = 0; h < 2; ++h) {
;             unsigned cv[8];
; #pragma unroll
;             for (unsigned j = 0; j < 8; ++j) cv[j] = xb_ld(&bar[XB_XCNT(8u * h + j)]);
; #pragma unroll
;             for (unsigned j = 0; j < 8; ++j) { sum += cv[j]; cnt += (cv[j] > 0u) ? 1u : 0u; if (8u * h + j == x) mine = cv[j]; }
;         }
;         if (sum == G) break;
;         __builtin_amdgcn_s_sleep(1);
;         if ((++sp & 255u) == 0u) { if (xb_ld(&bar[XB_TMO])) break; if (sp > XB_SPIN_CAP) { atomicAdd(&bar[XB_TMO], 1u); break; } }
;     }
;     nloc = mine > 0u ? mine : 1u; nx = cnt > 0u ? cnt : 1u;
.LBB0_227:
	s_lshl_b32 s8, s15, 9
	s_lshl_b64 s[0:1], s[8:9], 2
	s_add_u32 s0, s48, s0
	s_addc_u32 s1, s49, s1
	global_load_dword v0, v2, s[0:1] offset:1024 sc1
	global_load_dword v1, v2, s[0:1] offset:1280 sc1
	global_load_dword v6, v2, s[0:1] offset:1536 sc1
	global_load_dword v7, v2, s[0:1] offset:1792 sc1
	global_load_dword v8, v2, s[0:1] offset:2048 sc1
	global_load_dword v9, v2, s[0:1] offset:2304 sc1
	global_load_dword v10, v2, s[0:1] offset:2560 sc1
	global_load_dword v11, v2, s[0:1] offset:2816 sc1
	s_lshl_b32 s8, s15, 3
	s_cmp_eq_u32 s8, s33
	s_cselect_b64 vcc, -1, 0
	s_or_b32 s0, s8, 1
	s_cmp_eq_u32 s0, s33
	s_mov_b32 s15, 1
	s_waitcnt vmcnt(7)
	v_cmp_ne_u32_e64 s[0:1], 0, v0
	v_add_u32_e32 v5, v0, v5
	s_nop 0
	v_cndmask_b32_e64 v12, 0, 1, s[0:1]
	v_cndmask_b32_e32 v0, v4, v0, vcc
	s_waitcnt vmcnt(6)
	v_cmp_ne_u32_e32 vcc, 0, v1
	s_cselect_b64 s[0:1], -1, 0
	s_or_b32 s16, s8, 2
	s_waitcnt vmcnt(5)
	v_cmp_ne_u32_e64 s[4:5], 0, v6
	v_addc_co_u32_e32 v3, vcc, v3, v12, vcc
	s_cmp_eq_u32 s16, s33
	v_cndmask_b32_e64 v4, 0, 1, s[4:5]
	v_cndmask_b32_e64 v0, v0, v1, s[0:1]
	s_waitcnt vmcnt(4)
	v_cmp_ne_u32_e32 vcc, 0, v7
	s_cselect_b64 s[0:1], -1, 0
	s_waitcnt vmcnt(3)
	v_cmp_ne_u32_e64 s[4:5], 0, v8
	v_cndmask_b32_e64 v0, v0, v6, s[0:1]
	v_addc_co_u32_e32 v3, vcc, v3, v4, vcc
	s_or_b32 s0, s8, 3
	v_cndmask_b32_e64 v13, 0, 1, s[4:5]
	s_waitcnt vmcnt(2)
	v_cmp_ne_u32_e32 vcc, 0, v9
	s_cmp_eq_u32 s0, s33
	s_waitcnt vmcnt(1)
	v_cmp_ne_u32_e64 s[4:5], 0, v10
	v_addc_co_u32_e32 v3, vcc, v3, v13, vcc
	s_cselect_b64 s[0:1], -1, 0
	v_cndmask_b32_e64 v14, 0, 1, s[4:5]
	s_waitcnt vmcnt(0)
	v_cmp_ne_u32_e32 vcc, 0, v11
	v_cndmask_b32_e64 v0, v0, v7, s[0:1]
	s_or_b32 s0, s8, 4
	v_addc_co_u32_e32 v3, vcc, v3, v14, vcc
	s_cmp_eq_u32 s0, s33
	s_cselect_b64 vcc, -1, 0
	s_or_b32 s0, s8, 5
	v_add_u32_e32 v5, v5, v1
	s_cmp_eq_u32 s0, s33
	v_add_u32_e32 v1, v5, v6
	v_cndmask_b32_e32 v0, v0, v8, vcc
	s_cselect_b64 vcc, -1, 0
	s_or_b32 s0, s8, 6
	v_add_u32_e32 v1, v1, v7
	s_cmp_eq_u32 s0, s33
	v_add_u32_e32 v1, v1, v8
	v_cndmask_b32_e32 v0, v0, v9, vcc
	s_cselect_b64 vcc, -1, 0
	s_or_b32 s0, s8, 7
	v_add_u32_e32 v1, v1, v9
	s_cmp_eq_u32 s0, s33
	v_add_u32_e32 v1, v1, v10
	v_cndmask_b32_e32 v0, v0, v10, vcc
	s_cselect_b64 vcc, -1, 0
	v_add_u32_e32 v5, v1, v11
	v_cndmask_b32_e32 v4, v0, v11, vcc
	s_and_b64 vcc, exec, s[12:13]
	s_mov_b64 s[12:13], 0
	s_cbranch_vccnz .LBB0_227
	v_cmp_eq_u32_e32 vcc, s2, v5
	s_mov_b64 s[0:1], -1
	s_mov_b64 s[4:5], -1
	s_cbranch_vccnz .LBB0_225
	s_add_i32 s14, s14, 1
	s_and_b32 s4, s14, 0xff
	s_cmp_eq_u32 s4, 0
	s_cselect_b64 s[4:5], -1, 0
	s_and_b64 vcc, exec, s[4:5]
	s_sleep 3
	s_cbranch_vccz .LBB0_225
	global_load_dword v0, v2, s[10:11] sc1
	s_waitcnt vmcnt(0)
	v_cmp_eq_u32_e32 vcc, 0, v0
	s_cbranch_vccz .LBB0_225
	s_cmp_gt_u32 s14, 0x40000
	s_mov_b64 s[0:1], 0
	s_cselect_b64 s[4:5], -1, 0
	s_branch .LBB0_225

; DEV unsigned xb_ld(unsigned* p) { return __hip_atomic_load(p, __ATOMIC_RELAXED, __HIP_MEMORY_SCOPE_AGENT); }
; DEV void xcd_barrier_complete(unsigned* bar, unsigned x, unsigned& nloc, unsigned& nx) {
;     const unsigned G = gridDim.x * gridDim.y * gridDim.z;
;     unsigned sum, cnt, mine, sp = 0u;
;     for (;;) {
;         sum = 0u; cnt = 0u; mine = 0u;
; #pragma nounroll
;         for (unsigned h = 0; h < 2; ++h) {
;             unsigned cv[8];
; #pragma unroll
;             for (unsigned j = 0; j < 8; ++j) cv[j] = xb_ld(&bar[XB_XCNT(8u * h + j)]);
; #pragma unroll
;             for (unsigned j = 0; j < 8; ++j) { sum += cv[j]; cnt += (cv[j] > 0u) ? 1u : 0u; if (8u * h + j == x) mine = cv[j]; }
;         }
;         if (sum == G) break;
;         __builtin_amdgcn_s_sleep(1);
;         if ((++sp & 255u) == 0u) { if (xb_ld(&bar[XB_TMO])) break; if (sp > XB_SPIN_CAP) { atomicAdd(&bar[XB_TMO], 1u); break; } }
;     }
;     nloc = mine > 0u ? mine : 1u; nx = cnt > 0u ? cnt : 1u;
.LBB0_383:
	s_lshl_b32 s12, s0, 9
	s_lshl_b64 s[4:5], s[12:13], 2
	s_add_u32 s4, s48, s4
	s_addc_u32 s5, s49, s5
	global_load_dword v0, v2, s[4:5] offset:1024 sc1
	global_load_dword v1, v2, s[4:5] offset:1280 sc1
	global_load_dword v6, v2, s[4:5] offset:1536 sc1
	global_load_dword v7, v2, s[4:5] offset:1792 sc1
	global_load_dword v8, v2, s[4:5] offset:2048 sc1
	global_load_dword v9, v2, s[4:5] offset:2304 sc1
	global_load_dword v10, v2, s[4:5] offset:2560 sc1
	global_load_dword v11, v2, s[4:5] offset:2816 sc1
	s_lshl_b32 s1, s0, 3
	s_cmp_eq_u32 s1, s33
	s_cselect_b64 vcc, -1, 0
	s_or_b32 s4, s1, 1
	s_cmp_eq_u32 s4, s33
	s_mov_b32 s0, 1
	s_waitcnt vmcnt(7)
	v_cmp_ne_u32_e64 s[4:5], 0, v0
	v_add_u32_e32 v5, v0, v5
	s_nop 0
	v_cndmask_b32_e64 v12, 0, 1, s[4:5]
	v_cndmask_b32_e32 v0, v4, v0, vcc
	s_waitcnt vmcnt(6)
	v_cmp_ne_u32_e32 vcc, 0, v1
	s_cselect_b64 s[4:5], -1, 0
	s_or_b32 s12, s1, 2
	s_waitcnt vmcnt(5)
	v_cmp_ne_u32_e64 s[6:7], 0, v6
	v_addc_co_u32_e32 v3, vcc, v3, v12, vcc
	s_cmp_eq_u32 s12, s33
	v_cndmask_b32_e64 v4, 0, 1, s[6:7]
	v_cndmask_b32_e64 v0, v0, v1, s[4:5]
	s_waitcnt vmcnt(4)
	v_cmp_ne_u32_e32 vcc, 0, v7
	s_cselect_b64 s[4:5], -1, 0
	s_waitcnt vmcnt(3)
	v_cmp_ne_u32_e64 s[6:7], 0, v8
	v_cndmask_b32_e64 v0, v0, v6, s[4:5]
	v_addc_co_u32_e32 v3, vcc, v3, v4, vcc
	s_or_b32 s4, s1, 3
	v_cndmask_b32_e64 v13, 0, 1, s[6:7]
	s_waitcnt vmcnt(2)
	v_cmp_ne_u32_e32 vcc, 0, v9
	s_cmp_eq_u32 s4, s33
	s_waitcnt vmcnt(1)
	v_cmp_ne_u32_e64 s[6:7], 0, v10
	v_addc_co_u32_e32 v3, vcc, v3, v13, vcc
	s_cselect_b64 s[4:5], -1, 0
	v_cndmask_b32_e64 v14, 0, 1, s[6:7]
	s_waitcnt vmcnt(0)
	v_cmp_ne_u32_e32 vcc, 0, v11
	v_cndmask_b32_e64 v0, v0, v7, s[4:5]
	s_or_b32 s4, s1, 4
	v_addc_co_u32_e32 v3, vcc, v3, v14, vcc
	s_cmp_eq_u32 s4, s33
	s_cselect_b64 vcc, -1, 0
	s_or_b32 s4, s1, 5
	v_add_u32_e32 v5, v5, v1
	s_cmp_eq_u32 s4, s33
	v_add_u32_e32 v1, v5, v6
	v_cndmask_b32_e32 v0, v0, v8, vcc
	s_cselect_b64 vcc, -1, 0
	s_or_b32 s4, s1, 6
	v_add_u32_e32 v1, v1, v7
	s_cmp_eq_u32 s4, s33
	v_add_u32_e32 v1, v1, v8
	v_cndmask_b32_e32 v0, v0, v9, vcc
	s_cselect_b64 vcc, -1, 0
	s_or_b32 s1, s1, 7
	v_add_u32_e32 v1, v1, v9
	s_cmp_eq_u32 s1, s33
	v_add_u32_e32 v1, v1, v10
	v_cndmask_b32_e32 v0, v0, v10, vcc
	s_cselect_b64 vcc, -1, 0
	v_add_u32_e32 v5, v1, v11
	v_cndmask_b32_e32 v4, v0, v11, vcc
	s_and_b64 vcc, exec, s[14:15]
	s_mov_b64 s[14:15], 0
	s_cbranch_vccnz .LBB0_383
	v_cmp_eq_u32_e32 vcc, s2, v5
	s_mov_b64 s[0:1], -1
	s_mov_b64 s[4:5], -1
	s_cbranch_vccnz .LBB0_381
	s_add_i32 s16, s16, 1
	s_and_b32 s4, s16, 0xff
	s_cmp_eq_u32 s4, 0
	s_cselect_b64 s[4:5], -1, 0
	s_and_b64 vcc, exec, s[4:5]
	s_sleep 3
	s_cbranch_vccz .LBB0_381
	global_load_dword v0, v2, s[10:11] sc1
	s_waitcnt vmcnt(0)
	v_cmp_eq_u32_e32 vcc, 0, v0
	s_cbranch_vccz .LBB0_381
	s_cmp_gt_u32 s16, 0x40000
	s_mov_b64 s[0:1], 0
	s_cselect_b64 s[4:5], -1, 0
	s_branch .LBB0_381

.LBB0_501:
	global_load_dword v0, v96, s[10:11] sc1
	s_mov_b64 s[0:1], -1
	s_mov_b64 s[12:13], -1
	s_waitcnt vmcnt(0)
	v_cmp_lt_u32_e32 vcc, 3, v0
	s_cbranch_vccnz .LBB0_500
	s_sleep 3
	global_load_dword v0, v96, s[10:11] sc1
	s_waitcnt vmcnt(0)
	v_cmp_gt_u32_e32 vcc, 4, v0
	s_cbranch_vccz .LBB0_500
	s_sleep 3
	global_load_dword v0, v96, s[10:11] sc1
	s_waitcnt vmcnt(0)
	v_cmp_gt_u32_e32 vcc, 4, v0
	s_cbranch_vccz .LBB0_500
	s_sleep 3
	global_load_dword v0, v96, s[10:11] sc1
	s_waitcnt vmcnt(0)
	v_cmp_gt_u32_e32 vcc, 4, v0
	s_cbranch_vccz .LBB0_500
	s_sleep 3
	global_load_dword v0, v96, s[10:11] sc1
	s_waitcnt vmcnt(0)
	v_cmp_gt_u32_e32 vcc, 4, v0
	s_cbranch_vccz .LBB0_500
	s_add_i32 s2, s2, -5
	s_cmp_eq_u32 s2, 0
	s_mov_b64 s[0:1], 0
	s_cselect_b64 s[12:13], -1, 0
	s_sleep 3
	s_branch .LBB0_500

; DEV unsigned xb_ld(unsigned* p) { return __hip_atomic_load(p, __ATOMIC_RELAXED, __HIP_MEMORY_SCOPE_AGENT); }
; DEV void xcd_barrier_complete(unsigned* bar, unsigned x, unsigned& nloc, unsigned& nx) {
;     const unsigned G = gridDim.x * gridDim.y * gridDim.z;
;     unsigned sum, cnt, mine, sp = 0u;
;     for (;;) {
;         sum = 0u; cnt = 0u; mine = 0u;
; #pragma nounroll
;         for (unsigned h = 0; h < 2; ++h) {
;             unsigned cv[8];
; #pragma unroll
;             for (unsigned j = 0; j < 8; ++j) cv[j] = xb_ld(&bar[XB_XCNT(8u * h + j)]);
; #pragma unroll
;             for (unsigned j = 0; j < 8; ++j) { sum += cv[j]; cnt += (cv[j] > 0u) ? 1u : 0u; if (8u * h + j == x) mine = cv[j]; }
;         }
;         if (sum == G) break;
;         __builtin_amdgcn_s_sleep(1);
;         if ((++sp & 255u) == 0u) { if (xb_ld(&bar[XB_TMO])) break; if (sp > XB_SPIN_CAP) { atomicAdd(&bar[XB_TMO], 1u); break; } }
;     }
;     nloc = mine > 0u ? mine : 1u; nx = cnt > 0u ? cnt : 1u;
.LBB0_537:
	s_lshl_b32 s10, s0, 9
	s_lshl_b64 s[4:5], s[10:11], 2
	s_add_u32 s4, s48, s4
	s_addc_u32 s5, s49, s5
	global_load_dword v0, v2, s[4:5] offset:1024 sc1
	global_load_dword v1, v2, s[4:5] offset:1280 sc1
	global_load_dword v6, v2, s[4:5] offset:1536 sc1
	global_load_dword v7, v2, s[4:5] offset:1792 sc1
	global_load_dword v8, v2, s[4:5] offset:2048 sc1
	global_load_dword v9, v2, s[4:5] offset:2304 sc1
	global_load_dword v10, v2, s[4:5] offset:2560 sc1
	global_load_dword v11, v2, s[4:5] offset:2816 sc1
	s_lshl_b32 s1, s0, 3
	s_cmp_eq_u32 s1, s33
	s_cselect_b64 vcc, -1, 0
	s_or_b32 s4, s1, 1
	s_cmp_eq_u32 s4, s33
	s_mov_b32 s0, 1
	s_waitcnt vmcnt(7)
	v_cmp_ne_u32_e64 s[4:5], 0, v0
	v_add_u32_e32 v5, v0, v5
	s_nop 0
	v_cndmask_b32_e64 v12, 0, 1, s[4:5]
	v_cndmask_b32_e32 v0, v4, v0, vcc
	s_waitcnt vmcnt(6)
	v_cmp_ne_u32_e32 vcc, 0, v1
	s_cselect_b64 s[4:5], -1, 0
	s_or_b32 s10, s1, 2
	s_waitcnt vmcnt(5)
	v_cmp_ne_u32_e64 s[6:7], 0, v6
	v_addc_co_u32_e32 v3, vcc, v3, v12, vcc
	s_cmp_eq_u32 s10, s33
	v_cndmask_b32_e64 v4, 0, 1, s[6:7]
	v_cndmask_b32_e64 v0, v0, v1, s[4:5]
	s_waitcnt vmcnt(4)
	v_cmp_ne_u32_e32 vcc, 0, v7
	s_cselect_b64 s[4:5], -1, 0
	s_waitcnt vmcnt(3)
	v_cmp_ne_u32_e64 s[6:7], 0, v8
	v_cndmask_b32_e64 v0, v0, v6, s[4:5]
	v_addc_co_u32_e32 v3, vcc, v3, v4, vcc
	s_or_b32 s4, s1, 3
	v_cndmask_b32_e64 v13, 0, 1, s[6:7]
	s_waitcnt vmcnt(2)
	v_cmp_ne_u32_e32 vcc, 0, v9
	s_cmp_eq_u32 s4, s33
	s_waitcnt vmcnt(1)
	v_cmp_ne_u32_e64 s[6:7], 0, v10
	v_addc_co_u32_e32 v3, vcc, v3, v13, vcc
	s_cselect_b64 s[4:5], -1, 0
	v_cndmask_b32_e64 v14, 0, 1, s[6:7]
	s_waitcnt vmcnt(0)
	v_cmp_ne_u32_e32 vcc, 0, v11
	v_cndmask_b32_e64 v0, v0, v7, s[4:5]
	s_or_b32 s4, s1, 4
	v_addc_co_u32_e32 v3, vcc, v3, v14, vcc
	s_cmp_eq_u32 s4, s33
	s_cselect_b64 vcc, -1, 0
	s_or_b32 s4, s1, 5
	v_add_u32_e32 v5, v5, v1
	s_cmp_eq_u32 s4, s33
	v_add_u32_e32 v1, v5, v6
	v_cndmask_b32_e32 v0, v0, v8, vcc
	s_cselect_b64 vcc, -1, 0
	s_or_b32 s4, s1, 6
	v_add_u32_e32 v1, v1, v7
	s_cmp_eq_u32 s4, s33
	v_add_u32_e32 v1, v1, v8
	v_cndmask_b32_e32 v0, v0, v9, vcc
	s_cselect_b64 vcc, -1, 0
	s_or_b32 s1, s1, 7
	v_add_u32_e32 v1, v1, v9
	s_cmp_eq_u32 s1, s33
	v_add_u32_e32 v1, v1, v10
	v_cndmask_b32_e32 v0, v0, v10, vcc
	s_cselect_b64 vcc, -1, 0
	v_add_u32_e32 v5, v1, v11
	v_cndmask_b32_e32 v4, v0, v11, vcc
	s_and_b64 vcc, exec, s[14:15]
	s_mov_b64 s[14:15], 0
	s_cbranch_vccnz .LBB0_537
	v_cmp_eq_u32_e32 vcc, s2, v5
	s_mov_b64 s[0:1], -1
	s_mov_b64 s[4:5], -1
	s_cbranch_vccnz .LBB0_535
	s_add_i32 s16, s16, 1
	s_and_b32 s4, s16, 0xff
	s_cmp_eq_u32 s4, 0
	s_cselect_b64 s[4:5], -1, 0
	s_and_b64 vcc, exec, s[4:5]
	s_sleep 3
	s_cbranch_vccz .LBB0_535
	global_load_dword v0, v2, s[12:13] sc1
	s_waitcnt vmcnt(0)
	v_cmp_eq_u32_e32 vcc, 0, v0
	s_cbranch_vccz .LBB0_535
	s_cmp_gt_u32 s16, 0x40000
	s_mov_b64 s[0:1], 0
	s_cselect_b64 s[4:5], -1, 0
	s_branch .LBB0_535

; template <int SKIP>
; DEV void mlstm_phase(LAS char* shm, const bf16_t* q, const bf16_t* k, const bf16_t* v, const float* gpart, const float* b_ig, const float* b_fg, bf16_t* hc, const bool pre) {
;     ...
;             if (wid < 4) asm volatile("s_waitcnt vmcnt(1)" ::: "memory");
;             else asm volatile("s_waitcnt vmcnt(0)" ::: "memory");
;     ...
;             m_prev = __int_as_float(__builtin_amdgcn_readfirstlane(__float_as_int(btot + mxc)));
; #pragma unroll
;             for (int ks = 0; ks < 8; ++ks) qfr[ks] = qnx[ks];
.LBB0_635:
	s_and_b64 vcc, exec, s[84:85]
	s_cbranch_vccnz .Lml0_w47
	s_waitcnt vmcnt(1)
	s_branch .Lml0_go
.Lml0_w47:
	s_waitcnt vmcnt(0)
.Lml0_go:
	s_addk_i32 s40, 0x100
	v_mov_b32_e32 v0, s42
	s_add_u32 s38, s38, 0x8000
	v_add_f32_e32 v0, s43, v0
	s_addc_u32 s39, s39, 0
	s_add_i32 s41, s41, 8
	v_mov_b64_e32 v[38:39], v[98:99]
	v_mov_b64_e32 v[34:35], v[90:91]
	v_mov_b64_e32 v[30:31], v[82:83]
	v_mov_b64_e32 v[10:11], v[78:79]
	v_mov_b64_e32 v[26:27], v[106:107]
	v_mov_b64_e32 v[22:23], v[102:103]
	v_mov_b64_e32 v[14:15], v[94:95]
	v_mov_b64_e32 v[18:19], v[86:87]
	v_readfirstlane_b32 s28, v0
	v_lshl_add_u64 v[168:169], v[168:169], 0, s[90:91]
	v_lshl_add_u64 v[172:173], v[172:173], 0, s[90:91]
	v_lshl_add_u64 v[174:175], v[174:175], 0, s[90:91]
	s_cmp_eq_u32 s40, 0
	v_mov_b64_e32 v[40:41], v[100:101]
	v_mov_b64_e32 v[36:37], v[92:93]
	v_mov_b64_e32 v[32:33], v[84:85]
	v_mov_b64_e32 v[12:13], v[80:81]
	v_mov_b64_e32 v[28:29], v[108:109]
	v_mov_b64_e32 v[24:25], v[104:105]
	v_mov_b64_e32 v[16:17], v[96:97]
	v_mov_b64_e32 v[20:21], v[88:89]
	s_cbranch_scc1 .LBB0_593

; #define LAS __attribute__((address_space(3)))
; #define MLK_ISSUE(chunk_off_elems, buf) do { const char* kg_ = (const char*)(k + (chunk_off_elems)); _Pragma("unroll") for (int i_ = 0; i_ < 4; ++i_) \
;             __builtin_amdgcn_global_load_lds((const unsigned*)(kg_ + kvoff + (size_t)i_ * 16 * DM * 2), (LAS unsigned*)(shm + (buf) * 32768 + (i_ * 8 + wid) * 1024), 16, 0, 0); } while (0)
; DEV void mlstm_b_wave(LAS char* shm, const bf16x8 (&qfr)[8], int fr, int fq, f32x4 (&nacc)[3]) {
;     constexpr int CB = 81408, RS = 528;
;     const LAS char* cbp = shm + CB + fr * RS + fq * 16;
;     bf16x8 cf[3];
; #pragma unroll
;     for (int vt = 0; vt < 3; ++vt) cf[vt] = *(const LAS bf16x8*)(cbp + vt * 16 * RS);
; #pragma unroll
;     for (int ks = 0; ks < 8; ++ks) {
;         bf16x8 cn[3] = {cf[0], cf[1], cf[2]};
;         if (ks < 7) {
; #pragma unroll
;             for (int vt = 0; vt < 3; ++vt) cn[vt] = *(const LAS bf16x8*)(cbp + vt * 16 * RS + (ks + 1) * 64);
;         }
; #pragma unroll
;         for (int vt = 0; vt < 3; ++vt) nacc[vt] = __builtin_amdgcn_mfma_f32_16x16x32_bf16(qfr[ks], cf[vt], nacc[vt], 0, 0, 0);
; #pragma unroll
;         for (int vt = 0; vt < 3; ++vt) cf[vt] = cn[vt];
;     }
; }
; template <int SKIP>
; DEV void mlstm_phase(LAS char* shm, const bf16_t* q, const bf16_t* k, const bf16_t* v, const float* gpart, const float* b_ig, const float* b_fg, bf16_t* hc, const bool pre) {
;     ...
;             if (j + 1 < SEQ / CHUNK) {
;                 const size_t cn = cb + (size_t)CHUNK * DM;
;                 MLK_ISSUE(cn, (j + 1) & 1);
; #pragma unroll
;                 for (int ks = 0; ks < 8; ++ks) qnx[ks] = *(const bf16x8*)(qfb + (size_t)(j + 1) * 16384 + ks * 512);
;                 if (wid < 4) vv = *(const uint4*)(v + cn + (size_t)(tid >> 2) * DM + vs * 32 + (tid & 3) * 8);
;             }
.LBB0_650:
	s_waitcnt lgkmcnt(0)
	s_barrier
	s_and_b64 vcc, exec, s[84:85]
	s_cbranch_vccnz .Lpf0_done
	s_cmpk_eq_i32 s40, 0xff00
	s_cbranch_scc1 .Lpf0_done
	v_lshl_add_u64 v[0:1], v[168:169], 0, s[74:75]
	s_mov_b64 s[0:1], 0x2032000
	v_lshl_add_u64 v[4:5], v[0:1], 0, s[0:1]
	s_add_i32 s0, s38, 0x8000
	s_and_b32 s0, s0, 0x8000
	s_add_i32 s29, s65, s0
	s_mov_b32 m0, s29
	s_mov_b64 s[0:1], 0x203a000
	global_load_lds_dwordx4 v[4:5], off
	v_lshl_add_u64 v[4:5], v[0:1], 0, s[0:1]
	s_add_i32 m0, s29, 0x2000
	s_mov_b64 s[0:1], 0x2042000
	global_load_lds_dwordx4 v[4:5], off
	v_lshl_add_u64 v[4:5], v[0:1], 0, s[0:1]
	s_add_i32 m0, s29, 0x4000
	s_mov_b64 s[0:1], 0x204a000
	global_load_lds_dwordx4 v[4:5], off
	v_lshl_add_u64 v[0:1], v[0:1], 0, s[0:1]
	s_add_i32 m0, s29, 0x6000
	s_mov_b32 s0, 0xc074000
	global_load_lds_dwordx4 v[0:1], off
	v_lshl_add_u64 v[0:1], v[170:171], 0, s[38:39]
	v_add_co_u32_e32 v4, vcc, s0, v0
	s_nop 1
	v_addc_co_u32_e32 v5, vcc, 0, v1, vcc
	v_add_co_u32_e32 v0, vcc, 0xc075000, v0
	global_load_dwordx4 v[98:101], v[4:5], off
	global_load_dwordx4 v[90:93], v[4:5], off offset:1024
	global_load_dwordx4 v[82:85], v[4:5], off offset:2048
	global_load_dwordx4 v[78:81], v[4:5], off offset:3072
	v_addc_co_u32_e32 v1, vcc, 0, v1, vcc
	global_load_dwordx4 v[106:109], v[0:1], off
	global_load_dwordx4 v[102:105], v[0:1], off offset:1024
	global_load_dwordx4 v[94:97], v[0:1], off offset:2048
	global_load_dwordx4 v[86:89], v[0:1], off offset:3072
	v_lshl_add_u64 v[0:1], v[174:175], 0, s[74:75]
	v_add_co_u32_e32 v0, vcc, 0xa07a000, v0
	s_nop 1
	v_addc_co_u32_e32 v1, vcc, 0, v1, vcc
	global_load_dwordx4 v[6:9], v[0:1], off
.Lpf0_done:
	v_add_u32_e32 v2, s40, v204
	s_mov_b64 s[0:1], -1
	s_and_b64 vcc, exec, s[84:85]
	v_add_u32_e32 v228, 0x23500, v2
	s_cbranch_vccz .LBB0_652
	ds_read_b128 v[110:113], v209
	ds_read_b128 v[114:117], v209 offset:8448
	ds_read_b128 v[118:121], v209 offset:16896
	ds_read_b128 v[122:125], v209 offset:64
	ds_read_b128 v[126:129], v209 offset:8512
	ds_read_b128 v[130:133], v209 offset:16960
	s_waitcnt lgkmcnt(3)
	v_mfma_f32_16x16x32_bf16 v[110:113], v[38:41], v[110:113], 0
	ds_read_b128 v[134:137], v209 offset:128
	ds_read_b128 v[138:141], v209 offset:8576
	ds_read_b128 v[142:145], v209 offset:17024
	s_mov_b64 s[0:1], 0
	v_mfma_f32_16x16x32_bf16 v[114:117], v[38:41], v[114:117], 0
	v_mfma_f32_16x16x32_bf16 v[118:121], v[38:41], v[118:121], 0
	s_waitcnt lgkmcnt(3)
	v_mfma_f32_16x16x32_bf16 v[110:113], v[34:37], v[122:125], v[110:113]
	v_mfma_f32_16x16x32_bf16 v[114:117], v[34:37], v[126:129], v[114:117]
	v_mfma_f32_16x16x32_bf16 v[118:121], v[34:37], v[130:133], v[118:121]
	ds_read_b128 v[122:125], v209 offset:192
	ds_read_b128 v[126:129], v209 offset:8640
	ds_read_b128 v[130:133], v209 offset:17088
	s_waitcnt lgkmcnt(3)
	v_mfma_f32_16x16x32_bf16 v[110:113], v[30:33], v[134:137], v[110:113]
	v_mfma_f32_16x16x32_bf16 v[114:117], v[30:33], v[138:141], v[114:117]
	v_mfma_f32_16x16x32_bf16 v[118:121], v[30:33], v[142:145], v[118:121]
	ds_read_b128 v[134:137], v209 offset:256
	ds_read_b128 v[138:141], v209 offset:8704
	ds_read_b128 v[142:145], v209 offset:17152
	s_waitcnt lgkmcnt(3)
	v_mfma_f32_16x16x32_bf16 v[110:113], v[10:13], v[122:125], v[110:113]
	v_mfma_f32_16x16x32_bf16 v[114:117], v[10:13], v[126:129], v[114:117]
	v_mfma_f32_16x16x32_bf16 v[118:121], v[10:13], v[130:133], v[118:121]
	ds_read_b128 v[122:125], v209 offset:320
	ds_read_b128 v[126:129], v209 offset:8768
	ds_read_b128 v[130:133], v209 offset:17216
	s_waitcnt lgkmcnt(3)
	v_mfma_f32_16x16x32_bf16 v[110:113], v[26:29], v[134:137], v[110:113]
	v_mfma_f32_16x16x32_bf16 v[114:117], v[26:29], v[138:141], v[114:117]
	v_mfma_f32_16x16x32_bf16 v[118:121], v[26:29], v[142:145], v[118:121]
	ds_read_b128 v[134:137], v209 offset:384
	ds_read_b128 v[138:141], v209 offset:8832
	ds_read_b128 v[142:145], v209 offset:17280
	s_waitcnt lgkmcnt(3)
	v_mfma_f32_16x16x32_bf16 v[110:113], v[22:25], v[122:125], v[110:113]
	v_mfma_f32_16x16x32_bf16 v[114:117], v[22:25], v[126:129], v[114:117]
	v_mfma_f32_16x16x32_bf16 v[118:121], v[22:25], v[130:133], v[118:121]
	ds_read_b128 v[122:125], v209 offset:17344
	ds_read_b128 v[126:129], v209 offset:448
	ds_read_b128 v[130:133], v209 offset:8896
	s_waitcnt lgkmcnt(0)
	v_mfma_f32_16x16x32_bf16 v[110:113], v[14:17], v[134:137], v[110:113]
	v_mfma_f32_16x16x32_bf16 v[134:137], v[14:17], v[142:145], v[118:121]
	v_mfma_f32_16x16x32_bf16 v[118:121], v[18:21], v[126:129], v[110:113]
	s_nop 5
	ds_read_b128 v[110:113], v228
	v_mfma_f32_16x16x32_bf16 v[114:117], v[14:17], v[138:141], v[114:117]
	s_waitcnt lgkmcnt(0)
	v_max_f32_e32 v0, v110, v110
	v_max_f32_e32 v4, v111, v111
	v_max_f32_e32 v0, v227, v0
	v_max_f32_e32 v4, v227, v4
	v_sub_f32_e32 v0, s28, v0
	v_sub_f32_e32 v4, s28, v4
	v_max_f32_e32 v110, v112, v112
	v_max_f32_e32 v112, v113, v113
	v_mul_f32_e32 v0, 0x3fb8aa3b, v0
	v_mul_f32_e32 v4, 0x3fb8aa3b, v4
	v_max_f32_e32 v110, v227, v110
	v_max_f32_e32 v112, v227, v112
	v_mfma_f32_16x16x32_bf16 v[114:117], v[18:21], v[130:133], v[114:117]
	v_exp_f32_e32 v0, v0
	v_exp_f32_e32 v4, v4
	v_sub_f32_e32 v110, s28, v110
	v_mfma_f32_16x16x32_bf16 v[122:125], v[18:21], v[122:125], v[134:137]
	v_sub_f32_e32 v112, s28, v112
	v_mul_f32_e32 v110, 0x3fb8aa3b, v110
	v_mul_f32_e32 v112, 0x3fb8aa3b, v112
	v_exp_f32_e32 v110, v110
	v_exp_f32_e32 v112, v112
	v_mul_f32_e32 v1, v118, v0
	v_mul_f32_e32 v5, v119, v4
	v_mul_f32_e32 v126, v114, v0
	v_mul_f32_e32 v0, v122, v0
	ds_write2_b32 v219, v1, v126 offset1:16
	v_mul_f32_e32 v1, v115, v4
	ds_write2_b32 v219, v0, v5 offset0:32 offset1:52
	v_mul_f32_e32 v0, v123, v4
	v_mul_f32_e32 v111, v120, v110
	v_mul_f32_e32 v113, v121, v112
	v_mul_f32_e32 v126, v116, v110
	ds_write2_b32 v219, v1, v0 offset0:68 offset1:84
	v_mul_f32_e32 v0, v124, v110
	ds_write2_b32 v219, v111, v126 offset0:104 offset1:120
	v_mul_f32_e32 v111, v117, v112
	ds_write2_b32 v219, v0, v113 offset0:136 offset1:156
	v_mul_f32_e32 v0, v125, v112
	ds_write2_b32 v219, v111, v0 offset0:172 offset1:188
; template <int TT>
; DEV void mlstm_a_wave(LAS char* shm, const LAS char* kbuf, const bf16x8 (&qfr)[8], int fr, int fq, float m_prev, const LAS float* tpj, const LAS float* taj, f32x4 (&nacc)[3]) {
;     constexpr int VT = 67584, VRS = 96, NT = TT + 1;
;     const LAS char* kb = kbuf + fr * 512 + ((fq ^ (fr & 3)) << 4);
;     int xo[4];
; #pragma unroll
;     for (int b_ = 0; b_ < 4; ++b_) xo[b_] = ((b_ ^ (fr >> 2)) << 6);
;     ...
;     f32x4 sacc[NT];
; #pragma unroll
;     for (int jj = 0; jj < NT; ++jj) sacc[jj] = (f32x4){0.f, 0.f, 0.f, 0.f};
;     bf16x8 kf[NT];
; #pragma unroll
;     for (int jj = 0; jj < NT; ++jj) kf[jj] = *(const LAS bf16x8*)MLK_ADDR(jj, 0);
; #pragma unroll
;     for (int ks = 0; ks < 8; ++ks) {
;         bf16x8 kn[NT];
; #pragma unroll
;         for (int jj = 0; jj < NT; ++jj) kn[jj] = kf[jj];
;         if (ks < 7) {
; #pragma unroll
;             for (int jj = 0; jj < NT; ++jj) kn[jj] = *(const LAS bf16x8*)MLK_ADDR(jj, ks + 1);
;         }
; #pragma unroll
;         for (int jj = 0; jj < NT; ++jj) sacc[jj] = __builtin_amdgcn_mfma_f32_16x16x32_bf16(kf[jj], qfr[ks], sacc[jj], 0, 0, 0);
; #pragma unroll
;         for (int jj = 0; jj < NT; ++jj) kf[jj] = kn[jj];
;     }
;     ...
;     constexpr int NK = (TT >= 2) ? 2 : 1;
;     s16x4 vlo[NK][3], vhi[NK][3];
; #pragma unroll
;     for (int kk = 0; kk < NK; ++kk)
; #pragma unroll
;         for (int vt = 0; vt < 3; ++vt) {
;             vlo[kk][vt] = __builtin_amdgcn_ds_read_tr16_b64_v4i16((LAS s16x4*)(shm + VT + (32 * kk + 4 * fq + (fr >> 2)) * VRS + (16 * vt + 4 * (fr & 3)) * 2));
;             vhi[kk][vt] = __builtin_amdgcn_ds_read_tr16_b64_v4i16((LAS s16x4*)(shm + VT + (32 * kk + 16 + 4 * fq + (fr >> 2)) * VRS + (16 * vt + 4 * (fr & 3)) * 2));
;         }
;     const int t = 16 * TT + fr;
;     const float btm = -fmaxf(m_prev, tpj[t]);
;     f32x4 sm[2 * NK];
; #pragma unroll
;     for (int jj = 0; jj < 2 * NK; ++jj) {
;         if (jj < NT) {
;             const f32x4 a4 = *(const LAS f32x4*)(taj + 16 * jj + 4 * fq);
; #pragma unroll
;             for (int r = 0; r < 4; ++r) {
;                 const int s_ = 16 * jj + 4 * fq + r;
;                 sm[jj][r] = (jj < TT || s_ <= t) ? sacc[jj < NT ? jj : 0][r] * __expf(btm + a4[r]) : 0.f;
;             }
;         } else sm[jj] = (f32x4){0.f, 0.f, 0.f, 0.f};
;     }
; #pragma unroll
;     for (int kk = 0; kk < NK; ++kk) {
.LBB0_652:
	s_and_b32 s29, s38, 0x8000
	s_andn2_b64 vcc, exec, s[0:1]
	s_add_i32 s29, s29, 0
	s_cbranch_vccnz .LBB0_664
	v_add3_u32 v5, s29, v180, v181
	v_add_u32_e32 v4, v5, v182
	ds_read_b128 v[110:113], v4
	s_cmp_lt_i32 s67, 2
	s_mov_b64 s[0:1], -1
	s_cbranch_scc1 .LBB0_659
	s_cmp_gt_i32 s67, 2
	s_cbranch_scc0 .LBB0_656
	ds_read_b128 v[114:117], v4 offset:8192
	ds_read_b128 v[118:121], v4 offset:16384
	ds_read_b128 v[122:125], v4 offset:24576
	v_add_u32_e32 v0, v5, v183
	ds_read_b128 v[126:129], v0
	ds_read_b128 v[130:133], v0 offset:8192
	ds_read_b128 v[134:137], v0 offset:16384
	ds_read_b128 v[138:141], v0 offset:24576
	s_waitcnt lgkmcnt(4)
	v_mfma_f32_16x16x32_bf16 v[142:145], v[110:113], v[38:41], 0
	v_add_u32_e32 v1, v5, v184
	ds_read_b128 v[146:149], v1
	ds_read_b128 v[150:153], v1 offset:8192
	ds_read_b128 v[230:233], v1 offset:16384
	ds_read_b128 v[234:237], v1 offset:24576
	v_add_u32_e32 v229, v5, v185
	v_mfma_f32_16x16x32_bf16 v[114:117], v[114:117], v[38:41], 0
	s_mov_b64 s[0:1], 0
	v_mfma_f32_16x16x32_bf16 v[118:121], v[118:121], v[38:41], 0
	v_mfma_f32_16x16x32_bf16 v[122:125], v[122:125], v[38:41], 0
	s_waitcnt lgkmcnt(4)
	v_mfma_f32_16x16x32_bf16 v[126:129], v[126:129], v[34:37], v[142:145]
	v_mfma_f32_16x16x32_bf16 v[114:117], v[130:133], v[34:37], v[114:117]
	v_mfma_f32_16x16x32_bf16 v[118:121], v[134:137], v[34:37], v[118:121]
	v_mfma_f32_16x16x32_bf16 v[122:125], v[138:141], v[34:37], v[122:125]
	ds_read_b128 v[130:133], v229
	ds_read_b128 v[134:137], v229 offset:8192
	ds_read_b128 v[138:141], v229 offset:16384
	ds_read_b128 v[142:145], v229 offset:24576
	s_waitcnt lgkmcnt(4)
	v_mfma_f32_16x16x32_bf16 v[126:129], v[146:149], v[30:33], v[126:129]
	v_mfma_f32_16x16x32_bf16 v[114:117], v[150:153], v[30:33], v[114:117]
	v_mfma_f32_16x16x32_bf16 v[118:121], v[230:233], v[30:33], v[118:121]
	v_mfma_f32_16x16x32_bf16 v[122:125], v[234:237], v[30:33], v[122:125]
	ds_read_b128 v[146:149], v4 offset:256
	ds_read_b128 v[150:153], v4 offset:8448
	ds_read_b128 v[230:233], v4 offset:16640
	ds_read_b128 v[234:237], v4 offset:24832
	s_waitcnt lgkmcnt(4)
	v_mfma_f32_16x16x32_bf16 v[126:129], v[130:133], v[10:13], v[126:129]
	v_mfma_f32_16x16x32_bf16 v[114:117], v[134:137], v[10:13], v[114:117]
	v_mfma_f32_16x16x32_bf16 v[118:121], v[138:141], v[10:13], v[118:121]
	v_mfma_f32_16x16x32_bf16 v[122:125], v[142:145], v[10:13], v[122:125]
	ds_read_b128 v[130:133], v0 offset:256
	ds_read_b128 v[134:137], v0 offset:8448
	ds_read_b128 v[138:141], v0 offset:16640
	ds_read_b128 v[142:145], v0 offset:24832
	v_add_u32_e32 v0, v187, v186
	s_waitcnt lgkmcnt(4)
	v_mfma_f32_16x16x32_bf16 v[126:129], v[146:149], v[26:29], v[126:129]
	v_mfma_f32_16x16x32_bf16 v[114:117], v[150:153], v[26:29], v[114:117]
	v_mfma_f32_16x16x32_bf16 v[118:121], v[230:233], v[26:29], v[118:121]
	v_mfma_f32_16x16x32_bf16 v[122:125], v[234:237], v[26:29], v[122:125]
	ds_read_b128 v[146:149], v1 offset:256
	ds_read_b128 v[150:153], v1 offset:8448
	ds_read_b128 v[230:233], v1 offset:16640
	ds_read_b128 v[234:237], v1 offset:24832
	s_waitcnt lgkmcnt(4)
	v_mfma_f32_16x16x32_bf16 v[126:129], v[130:133], v[22:25], v[126:129]
	v_mfma_f32_16x16x32_bf16 v[114:117], v[134:137], v[22:25], v[114:117]
	v_mfma_f32_16x16x32_bf16 v[118:121], v[138:141], v[22:25], v[118:121]
	ds_read_b128 v[130:133], v229 offset:256
	ds_read_b128 v[134:137], v229 offset:8448
	ds_read_b128 v[138:141], v229 offset:16640
	ds_read_b128 v[242:245], v229 offset:24832
	v_mfma_f32_16x16x32_bf16 v[122:125], v[142:145], v[22:25], v[122:125]
	s_waitcnt lgkmcnt(4)
	v_mfma_f32_16x16x32_bf16 v[126:129], v[146:149], v[14:17], v[126:129]
	v_mfma_f32_16x16x32_bf16 v[114:117], v[150:153], v[14:17], v[114:117]
	v_mfma_f32_16x16x32_bf16 v[118:121], v[230:233], v[14:17], v[118:121]
	v_mfma_f32_16x16x32_bf16 v[122:125], v[234:237], v[14:17], v[122:125]
	s_waitcnt lgkmcnt(0)
	v_mfma_f32_16x16x32_bf16 v[130:133], v[130:133], v[18:21], v[126:129]
	v_mfma_f32_16x16x32_bf16 v[142:145], v[134:137], v[18:21], v[114:117]
	v_mfma_f32_16x16x32_bf16 v[146:149], v[138:141], v[18:21], v[118:121]
	v_mfma_f32_16x16x32_bf16 v[230:233], v[242:245], v[18:21], v[122:125]
	s_nop 0
	ds_read_b64_tr_b16 v[140:141], v0 offset:1536
	ds_read_b64_tr_b16 v[138:139], v0
	ds_read_b64_tr_b16 v[134:135], v0 offset:32
	ds_read_b64_tr_b16 v[136:137], v0 offset:1568
	ds_read_b64_tr_b16 v[126:127], v0 offset:64
	ds_read_b64_tr_b16 v[128:129], v0 offset:1600
	ds_read_b64_tr_b16 v[118:119], v0 offset:3072
	ds_read_b64_tr_b16 v[120:121], v0 offset:4608
	ds_read_b64_tr_b16 v[114:115], v0 offset:3104
	ds_read_b64_tr_b16 v[116:117], v0 offset:4640
	ds_read_b64_tr_b16 v[122:123], v0 offset:3136
	ds_read_b64_tr_b16 v[124:125], v0 offset:4672
	v_add_u32_e32 v0, s40, v203
	v_add_u32_e32 v0, 0x235c0, v0
	ds_read_b32 v0, v0
	s_waitcnt lgkmcnt(0)
	v_max_f32_e32 v0, v0, v0
	v_max_f32_e32 v229, v227, v0
	v_add_u32_e32 v0, s40, v202
	v_add_u32_e32 v1, 0x21500, v0
	ds_read_b128 v[150:153], v1
	v_add_u32_e32 v1, 0x21540, v0
	ds_read_b128 v[234:237], v1
	v_add_u32_e32 v1, 0x21580, v0
	v_add_u32_e32 v0, 0x215c0, v0
	ds_read_b128 v[242:245], v1
	ds_read_b128 v[246:249], v0
	s_waitcnt lgkmcnt(1)
	v_sub_f32_e32 v1, v243, v229
	s_waitcnt lgkmcnt(0)
; DEV unsigned pk2(float lo, float hi) { f32n2 v = {lo, hi}; bf16n2 b = __builtin_convertvector(v, bf16n2); return __builtin_bit_cast(unsigned, b); }
; #define LAS __attribute__((address_space(3)))
; template <int TT>
; DEV void mlstm_a_wave(LAS char* shm, const LAS char* kbuf, const bf16x8 (&qfr)[8], int fr, int fq, float m_prev, const LAS float* tpj, const LAS float* taj, f32x4 (&nacc)[3]) {
;     ...
;     const int t = 16 * TT + fr;
;     const float btm = -fmaxf(m_prev, tpj[t]);
;     f32x4 sm[2 * NK];
; #pragma unroll
;     for (int jj = 0; jj < 2 * NK; ++jj) {
;         if (jj < NT) {
;             const f32x4 a4 = *(const LAS f32x4*)(taj + 16 * jj + 4 * fq);
; #pragma unroll
;             for (int r = 0; r < 4; ++r) {
;                 const int s_ = 16 * jj + 4 * fq + r;
;                 sm[jj][r] = (jj < TT || s_ <= t) ? sacc[jj < NT ? jj : 0][r] * __expf(btm + a4[r]) : 0.f;
;             }
;         } else sm[jj] = (f32x4){0.f, 0.f, 0.f, 0.f};
;     }
; #pragma unroll
;     for (int kk = 0; kk < NK; ++kk) {
;         const u32x4 u = (u32x4){pk2(sm[2 * kk][0], sm[2 * kk][1]), pk2(sm[2 * kk][2], sm[2 * kk][3]), pk2(sm[2 * kk + 1][0], sm[2 * kk + 1][1]), pk2(sm[2 * kk + 1][2], sm[2 * kk + 1][3])};
;         const bf16x8 af = *(const bf16x8*)&u;
; #pragma unroll
;         for (int vt = 0; vt < 3; ++vt) {
;             bf16x8 bv8; bv8[0] = vlo[kk][vt][0]; bv8[1] = vlo[kk][vt][1]; bv8[2] = vlo[kk][vt][2]; bv8[3] = vlo[kk][vt][3];
;             bv8[4] = vhi[kk][vt][0]; bv8[5] = vhi[kk][vt][1]; bv8[6] = vhi[kk][vt][2]; bv8[7] = vhi[kk][vt][3];
;             nacc[vt] = __builtin_amdgcn_mfma_f32_16x16x32_bf16(af, bv8, nacc[vt], 0, 0, 0);
	v_sub_f32_e32 v0, v246, v229
	v_mul_f32_e32 v0, 0x3fb8aa3b, v0
	v_exp_f32_e32 v0, v0
	v_mul_f32_e32 v1, 0x3fb8aa3b, v1
	v_exp_f32_e32 v1, v1
	v_mul_f32_e32 v0, v230, v0
	v_cndmask_b32_e64 v230, v0, 0, s[6:7]
	v_sub_f32_e32 v0, v247, v229
	v_mul_f32_e32 v0, 0x3fb8aa3b, v0
	v_exp_f32_e32 v0, v0
	s_nop 0
	v_mul_f32_e32 v0, v231, v0
	v_cndmask_b32_e64 v231, 0, v0, s[8:9]
	v_sub_f32_e32 v0, v248, v229
	v_mul_f32_e32 v0, 0x3fb8aa3b, v0
	v_exp_f32_e32 v0, v0
	s_nop 0
	v_mul_f32_e32 v0, v232, v0
	v_cndmask_b32_e64 v232, v0, 0, s[10:11]
	v_sub_f32_e32 v0, v249, v229
	v_mul_f32_e32 v0, 0x3fb8aa3b, v0
	v_exp_f32_e32 v0, v0
	s_nop 0
	v_mul_f32_e32 v0, v233, v0
	v_cndmask_b32_e64 v233, v0, 0, s[12:13]
	v_sub_f32_e32 v0, v242, v229
	v_mul_f32_e32 v0, 0x3fb8aa3b, v0
	v_exp_f32_e32 v0, v0
	s_nop 0
	v_pk_mul_f32 v[0:1], v[146:147], v[0:1]
	v_sub_f32_e32 v146, v244, v229
	v_sub_f32_e32 v147, v245, v229
	v_mul_f32_e32 v146, 0x3fb8aa3b, v146
	v_mul_f32_e32 v147, 0x3fb8aa3b, v147
	v_exp_f32_e32 v146, v146
	v_exp_f32_e32 v147, v147
	s_nop 0
	v_pk_mul_f32 v[146:147], v[148:149], v[146:147]
	v_sub_f32_e32 v148, v234, v229
	v_sub_f32_e32 v149, v235, v229
	v_mul_f32_e32 v148, 0x3fb8aa3b, v148
	v_mul_f32_e32 v149, 0x3fb8aa3b, v149
	v_exp_f32_e32 v148, v148
	v_exp_f32_e32 v149, v149
	s_nop 0
	v_pk_mul_f32 v[142:143], v[142:143], v[148:149]
	v_sub_f32_e32 v148, v236, v229
	v_sub_f32_e32 v149, v237, v229
	v_mul_f32_e32 v148, 0x3fb8aa3b, v148
	v_mul_f32_e32 v149, 0x3fb8aa3b, v149
	v_exp_f32_e32 v148, v148
	v_exp_f32_e32 v149, v149
	s_nop 0
	v_pk_mul_f32 v[144:145], v[144:145], v[148:149]
	v_sub_f32_e32 v148, v150, v229
	v_sub_f32_e32 v149, v151, v229
	v_mul_f32_e32 v148, 0x3fb8aa3b, v148
	v_mul_f32_e32 v149, 0x3fb8aa3b, v149
	v_exp_f32_e32 v148, v148
	v_exp_f32_e32 v149, v149
	s_nop 0
	v_pk_mul_f32 v[130:131], v[130:131], v[148:149]
	v_sub_f32_e32 v148, v152, v229
	v_sub_f32_e32 v149, v153, v229
	v_mul_f32_e32 v148, 0x3fb8aa3b, v148
	v_mul_f32_e32 v149, 0x3fb8aa3b, v149
	v_exp_f32_e32 v148, v148
	v_exp_f32_e32 v149, v149
	v_cvt_pk_bf16_f32 v130, v130, v131
	v_pk_mul_f32 v[132:133], v[132:133], v[148:149]
	s_nop 0
	v_cvt_pk_bf16_f32 v131, v132, v133
	v_cvt_pk_bf16_f32 v132, v142, v143
	v_cvt_pk_bf16_f32 v133, v144, v145
	s_nop 1
	v_mfma_f32_16x16x32_bf16 v[138:141], v[130:133], v[138:141], 0
	v_mfma_f32_16x16x32_bf16 v[134:137], v[130:133], v[134:137], 0
	v_mfma_f32_16x16x32_bf16 v[126:129], v[130:133], v[126:129], 0
	v_cvt_pk_bf16_f32 v130, v0, v1
	v_cvt_pk_bf16_f32 v131, v146, v147
	v_cvt_pk_bf16_f32 v132, v230, v231
	v_cvt_pk_bf16_f32 v133, v232, v233
	s_nop 1
	v_mfma_f32_16x16x32_bf16 v[118:121], v[130:133], v[118:121], v[138:141]
	v_mfma_f32_16x16x32_bf16 v[114:117], v[130:133], v[114:117], v[134:137]
	v_mfma_f32_16x16x32_bf16 v[122:125], v[130:133], v[122:125], v[126:129]
; template <int TT>
; DEV void mlstm_a_wave(LAS char* shm, const LAS char* kbuf, const bf16x8 (&qfr)[8], int fr, int fq, float m_prev, const LAS float* tpj, const LAS float* taj, f32x4 (&nacc)[3]) {
;     constexpr int VT = 67584, VRS = 96, NT = TT + 1;
;     const LAS char* kb = kbuf + fr * 512 + ((fq ^ (fr & 3)) << 4);
;     int xo[4];
; #pragma unroll
;     for (int b_ = 0; b_ < 4; ++b_) xo[b_] = ((b_ ^ (fr >> 2)) << 6);
;     ...
;     f32x4 sacc[NT];
; #pragma unroll
;     for (int jj = 0; jj < NT; ++jj) sacc[jj] = (f32x4){0.f, 0.f, 0.f, 0.f};
;     bf16x8 kf[NT];
; #pragma unroll
;     for (int jj = 0; jj < NT; ++jj) kf[jj] = *(const LAS bf16x8*)MLK_ADDR(jj, 0);
; #pragma unroll
;     for (int ks = 0; ks < 8; ++ks) {
;         bf16x8 kn[NT];
; #pragma unroll
;         for (int jj = 0; jj < NT; ++jj) kn[jj] = kf[jj];
;         if (ks < 7) {
; #pragma unroll
;             for (int jj = 0; jj < NT; ++jj) kn[jj] = *(const LAS bf16x8*)MLK_ADDR(jj, ks + 1);
;         }
; #pragma unroll
;         for (int jj = 0; jj < NT; ++jj) sacc[jj] = __builtin_amdgcn_mfma_f32_16x16x32_bf16(kf[jj], qfr[ks], sacc[jj], 0, 0, 0);
; #pragma unroll
;         for (int jj = 0; jj < NT; ++jj) kf[jj] = kn[jj];
;     }
;     ...
;     constexpr int NK = (TT >= 2) ? 2 : 1;
;     s16x4 vlo[NK][3], vhi[NK][3];
; #pragma unroll
;     for (int kk = 0; kk < NK; ++kk)
; #pragma unroll
;         for (int vt = 0; vt < 3; ++vt) {
;             vlo[kk][vt] = __builtin_amdgcn_ds_read_tr16_b64_v4i16((LAS s16x4*)(shm + VT + (32 * kk + 4 * fq + (fr >> 2)) * VRS + (16 * vt + 4 * (fr & 3)) * 2));
;             vhi[kk][vt] = __builtin_amdgcn_ds_read_tr16_b64_v4i16((LAS s16x4*)(shm + VT + (32 * kk + 16 + 4 * fq + (fr >> 2)) * VRS + (16 * vt + 4 * (fr & 3)) * 2));
;         }
;     const int t = 16 * TT + fr;
;     const float btm = -fmaxf(m_prev, tpj[t]);
;     f32x4 sm[2 * NK];
; #pragma unroll
;     for (int jj = 0; jj < 2 * NK; ++jj) {
;         if (jj < NT) {
;             const f32x4 a4 = *(const LAS f32x4*)(taj + 16 * jj + 4 * fq);
; #pragma unroll
;             for (int r = 0; r < 4; ++r) {
;                 const int s_ = 16 * jj + 4 * fq + r;
;                 sm[jj][r] = (jj < TT || s_ <= t) ? sacc[jj < NT ? jj : 0][r] * __expf(btm + a4[r]) : 0.f;
;             }
;         } else sm[jj] = (f32x4){0.f, 0.f, 0.f, 0.f};
;     }
; #pragma unroll
;     for (int kk = 0; kk < NK; ++kk) {
.LBB0_656:
	s_andn2_b64 vcc, exec, s[0:1]
	s_cbranch_vccnz .LBB0_658
	s_nop 4
	ds_read_b128 v[114:117], v4 offset:8192
	ds_read_b128 v[118:121], v4 offset:16384
	v_add_u32_e32 v0, v5, v183
	ds_read_b128 v[122:125], v0
	ds_read_b128 v[126:129], v0 offset:8192
	ds_read_b128 v[130:133], v0 offset:16384
	s_waitcnt lgkmcnt(3)
	v_mfma_f32_16x16x32_bf16 v[134:137], v[110:113], v[38:41], 0
	v_add_u32_e32 v1, v5, v184
	ds_read_b128 v[138:141], v1
	ds_read_b128 v[142:145], v1 offset:8192
	ds_read_b128 v[146:149], v1 offset:16384
	v_add_u32_e32 v150, v5, v185
	v_mfma_f32_16x16x32_bf16 v[114:117], v[114:117], v[38:41], 0
	v_mfma_f32_16x16x32_bf16 v[118:121], v[118:121], v[38:41], 0
	s_waitcnt lgkmcnt(3)
	v_mfma_f32_16x16x32_bf16 v[122:125], v[122:125], v[34:37], v[134:137]
	v_mfma_f32_16x16x32_bf16 v[114:117], v[126:129], v[34:37], v[114:117]
	v_mfma_f32_16x16x32_bf16 v[118:121], v[130:133], v[34:37], v[118:121]
	ds_read_b128 v[126:129], v150
	ds_read_b128 v[130:133], v150 offset:8192
	ds_read_b128 v[134:137], v150 offset:16384
	s_waitcnt lgkmcnt(3)
	v_mfma_f32_16x16x32_bf16 v[122:125], v[138:141], v[30:33], v[122:125]
	v_mfma_f32_16x16x32_bf16 v[114:117], v[142:145], v[30:33], v[114:117]
	v_mfma_f32_16x16x32_bf16 v[118:121], v[146:149], v[30:33], v[118:121]
	ds_read_b128 v[138:141], v4 offset:256
	ds_read_b128 v[142:145], v4 offset:8448
	ds_read_b128 v[146:149], v4 offset:16640
	s_waitcnt lgkmcnt(3)
	v_mfma_f32_16x16x32_bf16 v[122:125], v[126:129], v[10:13], v[122:125]
	v_mfma_f32_16x16x32_bf16 v[114:117], v[130:133], v[10:13], v[114:117]
	v_mfma_f32_16x16x32_bf16 v[118:121], v[134:137], v[10:13], v[118:121]
	ds_read_b128 v[126:129], v0 offset:256
	ds_read_b128 v[130:133], v0 offset:8448
	ds_read_b128 v[134:137], v0 offset:16640
	v_add_u32_e32 v0, v187, v186
	s_waitcnt lgkmcnt(3)
	v_mfma_f32_16x16x32_bf16 v[122:125], v[138:141], v[26:29], v[122:125]
	v_mfma_f32_16x16x32_bf16 v[114:117], v[142:145], v[26:29], v[114:117]
	v_mfma_f32_16x16x32_bf16 v[118:121], v[146:149], v[26:29], v[118:121]
	ds_read_b128 v[138:141], v1 offset:256
	ds_read_b128 v[142:145], v1 offset:8448
	ds_read_b128 v[146:149], v1 offset:16640
	s_waitcnt lgkmcnt(3)
	v_mfma_f32_16x16x32_bf16 v[122:125], v[126:129], v[22:25], v[122:125]
	v_mfma_f32_16x16x32_bf16 v[114:117], v[130:133], v[22:25], v[114:117]
	v_mfma_f32_16x16x32_bf16 v[118:121], v[134:137], v[22:25], v[118:121]
	ds_read_b128 v[126:129], v150 offset:256
	ds_read_b128 v[130:133], v150 offset:8448
	ds_read_b128 v[134:137], v150 offset:16640
	s_waitcnt lgkmcnt(3)
	v_mfma_f32_16x16x32_bf16 v[122:125], v[138:141], v[14:17], v[122:125]
	v_mfma_f32_16x16x32_bf16 v[114:117], v[142:145], v[14:17], v[114:117]
	v_mfma_f32_16x16x32_bf16 v[118:121], v[146:149], v[14:17], v[118:121]
	s_waitcnt lgkmcnt(0)
	v_mfma_f32_16x16x32_bf16 v[142:145], v[126:129], v[18:21], v[122:125]
	v_mfma_f32_16x16x32_bf16 v[130:133], v[130:133], v[18:21], v[114:117]
	v_mfma_f32_16x16x32_bf16 v[146:149], v[134:137], v[18:21], v[118:121]
	s_nop 0
	ds_read_b64_tr_b16 v[140:141], v0 offset:1536
	ds_read_b64_tr_b16 v[138:139], v0
	ds_read_b64_tr_b16 v[134:135], v0 offset:32
	ds_read_b64_tr_b16 v[136:137], v0 offset:1568
	ds_read_b64_tr_b16 v[126:127], v0 offset:64
	ds_read_b64_tr_b16 v[128:129], v0 offset:1600
	ds_read_b64_tr_b16 v[118:119], v0 offset:3072
	ds_read_b64_tr_b16 v[120:121], v0 offset:4608
	ds_read_b64_tr_b16 v[114:115], v0 offset:3104
	ds_read_b64_tr_b16 v[116:117], v0 offset:4640
	ds_read_b64_tr_b16 v[122:123], v0 offset:3136
	ds_read_b64_tr_b16 v[124:125], v0 offset:4672
	v_add_u32_e32 v0, s40, v203
	v_add_u32_e32 v0, 0x23580, v0
	ds_read_b32 v0, v0
	s_waitcnt lgkmcnt(0)
	v_max_f32_e32 v0, v0, v0
	v_max_f32_e32 v229, v227, v0
	v_add_u32_e32 v0, s40, v202
	v_add_u32_e32 v1, 0x21500, v0
	ds_read_b128 v[150:153], v1
	v_add_u32_e32 v1, 0x21540, v0
	v_add_u32_e32 v0, 0x21580, v0
	ds_read_b128 v[230:233], v1
	ds_read_b128 v[234:237], v0
	s_waitcnt lgkmcnt(0)
	v_sub_f32_e32 v0, v234, v229
	v_mul_f32_e32 v0, 0x3fb8aa3b, v0
	v_exp_f32_e32 v0, v0
	v_sub_f32_e32 v1, v237, v229
	v_mul_f32_e32 v1, 0x3fb8aa3b, v1
	v_exp_f32_e32 v1, v1
	v_mul_f32_e32 v0, v146, v0
	v_cndmask_b32_e64 v234, v0, 0, s[6:7]
	v_sub_f32_e32 v0, v235, v229
	v_mul_f32_e32 v0, 0x3fb8aa3b, v0
	v_exp_f32_e32 v0, v0
	v_sub_f32_e32 v146, v150, v229
	v_mul_f32_e32 v146, 0x3fb8aa3b, v146
	v_exp_f32_e32 v146, v146
	v_mul_f32_e32 v0, v147, v0
	v_sub_f32_e32 v147, v151, v229
	v_mul_f32_e32 v147, 0x3fb8aa3b, v147
	v_exp_f32_e32 v147, v147
	v_cndmask_b32_e64 v235, v0, 0, s[14:15]
	v_sub_f32_e32 v0, v236, v229
	v_mul_f32_e32 v0, 0x3fb8aa3b, v0
	v_pk_mul_f32 v[142:143], v[142:143], v[146:147]
	v_sub_f32_e32 v146, v152, v229
	v_sub_f32_e32 v147, v153, v229
	v_mul_f32_e32 v146, 0x3fb8aa3b, v146
	v_mul_f32_e32 v147, 0x3fb8aa3b, v147
	v_exp_f32_e32 v146, v146
	v_exp_f32_e32 v147, v147
	v_exp_f32_e32 v0, v0
	v_pk_mul_f32 v[144:145], v[144:145], v[146:147]
	v_sub_f32_e32 v146, v230, v229
	v_sub_f32_e32 v147, v231, v229
	v_mul_f32_e32 v146, 0x3fb8aa3b, v146
	v_mul_f32_e32 v147, 0x3fb8aa3b, v147
	v_exp_f32_e32 v146, v146
	v_exp_f32_e32 v147, v147
	v_pk_mul_f32 v[0:1], v[148:149], v[0:1]
	v_pk_mul_f32 v[146:147], v[130:131], v[146:147]
	v_sub_f32_e32 v130, v232, v229
	v_sub_f32_e32 v131, v233, v229
	v_mul_f32_e32 v130, 0x3fb8aa3b, v130
	v_mul_f32_e32 v131, 0x3fb8aa3b, v131
	v_exp_f32_e32 v130, v130
	v_exp_f32_e32 v131, v131
	v_cvt_pk_bf16_f32 v0, v0, v1
	v_cndmask_b32_e64 v1, v0, 0, s[18:19]
	v_lshrrev_b32_e32 v0, 16, v0
	v_pk_mul_f32 v[148:149], v[132:133], v[130:131]
	v_cvt_pk_bf16_f32 v130, v142, v143
	v_cvt_pk_bf16_f32 v131, v144, v145
	v_cvt_pk_bf16_f32 v132, v146, v147
	v_cvt_pk_bf16_f32 v133, v148, v149
	v_cndmask_b32_e64 v0, v0, 0, s[16:17]
	s_nop 0
	v_mfma_f32_16x16x32_bf16 v[138:141], v[130:133], v[138:141], 0
	v_mfma_f32_16x16x32_bf16 v[134:137], v[130:133], v[134:137], 0
	v_mfma_f32_16x16x32_bf16 v[126:129], v[130:133], v[126:129], 0
	v_cvt_pk_bf16_f32 v130, v234, v235
	v_perm_b32 v131, v0, v1, s60
	v_mov_b32_e32 v132, v3
	v_mov_b32_e32 v133, v3
	s_nop 1
	v_mfma_f32_16x16x32_bf16 v[118:121], v[130:133], v[118:121], v[138:141]
	v_mfma_f32_16x16x32_bf16 v[114:117], v[130:133], v[114:117], v[134:137]
	v_mfma_f32_16x16x32_bf16 v[122:125], v[130:133], v[122:125], v[126:129]

; template <int TT>
; DEV void mlstm_a_wave(LAS char* shm, const LAS char* kbuf, const bf16x8 (&qfr)[8], int fr, int fq, float m_prev, const LAS float* tpj, const LAS float* taj, f32x4 (&nacc)[3]) {
;     constexpr int VT = 67584, VRS = 96, NT = TT + 1;
;     const LAS char* kb = kbuf + fr * 512 + ((fq ^ (fr & 3)) << 4);
;     int xo[4];
; #pragma unroll
;     for (int b_ = 0; b_ < 4; ++b_) xo[b_] = ((b_ ^ (fr >> 2)) << 6);
;     ...
;     f32x4 sacc[NT];
; #pragma unroll
;     for (int jj = 0; jj < NT; ++jj) sacc[jj] = (f32x4){0.f, 0.f, 0.f, 0.f};
;     bf16x8 kf[NT];
; #pragma unroll
;     for (int jj = 0; jj < NT; ++jj) kf[jj] = *(const LAS bf16x8*)MLK_ADDR(jj, 0);
; #pragma unroll
;     for (int ks = 0; ks < 8; ++ks) {
;         bf16x8 kn[NT];
; #pragma unroll
;         for (int jj = 0; jj < NT; ++jj) kn[jj] = kf[jj];
;         if (ks < 7) {
; #pragma unroll
;             for (int jj = 0; jj < NT; ++jj) kn[jj] = *(const LAS bf16x8*)MLK_ADDR(jj, ks + 1);
;         }
; #pragma unroll
;         for (int jj = 0; jj < NT; ++jj) sacc[jj] = __builtin_amdgcn_mfma_f32_16x16x32_bf16(kf[jj], qfr[ks], sacc[jj], 0, 0, 0);
; #pragma unroll
;         for (int jj = 0; jj < NT; ++jj) kf[jj] = kn[jj];
;     }
;     ...
;     constexpr int NK = (TT >= 2) ? 2 : 1;
;     s16x4 vlo[NK][3], vhi[NK][3];
; #pragma unroll
;     for (int kk = 0; kk < NK; ++kk)
; #pragma unroll
;         for (int vt = 0; vt < 3; ++vt) {
;             vlo[kk][vt] = __builtin_amdgcn_ds_read_tr16_b64_v4i16((LAS s16x4*)(shm + VT + (32 * kk + 4 * fq + (fr >> 2)) * VRS + (16 * vt + 4 * (fr & 3)) * 2));
;             vhi[kk][vt] = __builtin_amdgcn_ds_read_tr16_b64_v4i16((LAS s16x4*)(shm + VT + (32 * kk + 16 + 4 * fq + (fr >> 2)) * VRS + (16 * vt + 4 * (fr & 3)) * 2));
;         }
;     const int t = 16 * TT + fr;
;     const float btm = -fmaxf(m_prev, tpj[t]);
;     f32x4 sm[2 * NK];
; #pragma unroll
;     for (int jj = 0; jj < 2 * NK; ++jj) {
;         if (jj < NT) {
;             const f32x4 a4 = *(const LAS f32x4*)(taj + 16 * jj + 4 * fq);
; #pragma unroll
;             for (int r = 0; r < 4; ++r) {
;                 const int s_ = 16 * jj + 4 * fq + r;
;                 sm[jj][r] = (jj < TT || s_ <= t) ? sacc[jj < NT ? jj : 0][r] * __expf(btm + a4[r]) : 0.f;
;             }
;         } else sm[jj] = (f32x4){0.f, 0.f, 0.f, 0.f};
;     }
; #pragma unroll
;     for (int kk = 0; kk < NK; ++kk) {
.LBB0_659:
	s_andn2_b64 vcc, exec, s[0:1]
	s_cbranch_vccnz .LBB0_664
	v_add_u32_e32 v131, v5, v183
	v_add_u32_e32 v130, v5, v184
	v_add_u32_e32 v129, v5, v185
	v_add_u32_e32 v5, s40, v202
	s_mov_b64 s[0:1], -1
	s_cmp_eq_u32 s67, 1
	v_add_u32_e32 v127, v187, v186
	v_add_u32_e32 v128, s40, v203
	v_add_u32_e32 v126, 0x21500, v5
	s_cbranch_scc1 .LBB0_662
	ds_read_b128 v[114:117], v131
	ds_read_b128 v[122:125], v130
	s_waitcnt lgkmcnt(0)
	v_mfma_f32_16x16x32_bf16 v[118:121], v[110:113], v[38:41], 0
	v_add_u32_e32 v0, 0x23500, v128
	s_mov_b64 s[0:1], 0
	v_mfma_f32_16x16x32_bf16 v[114:117], v[114:117], v[34:37], v[118:121]
	s_nop 4
	ds_read_b128 v[118:121], v129
	v_mfma_f32_16x16x32_bf16 v[114:117], v[122:125], v[30:33], v[114:117]
	ds_read_b128 v[122:125], v4 offset:256
	s_waitcnt lgkmcnt(0)
	v_mfma_f32_16x16x32_bf16 v[114:117], v[118:121], v[10:13], v[114:117]
	ds_read_b128 v[118:121], v131 offset:256
	v_mfma_f32_16x16x32_bf16 v[114:117], v[122:125], v[26:29], v[114:117]
	ds_read_b128 v[122:125], v130 offset:256
	s_waitcnt lgkmcnt(0)
	v_mfma_f32_16x16x32_bf16 v[114:117], v[118:121], v[22:25], v[114:117]
	ds_read_b128 v[118:121], v129 offset:256
	v_mfma_f32_16x16x32_bf16 v[132:135], v[122:125], v[14:17], v[114:117]
	s_nop 0
	ds_read_b64_tr_b16 v[138:139], v127 offset:1536
	ds_read_b64_tr_b16 v[136:137], v127
	s_nop 2
	ds_read_b64_tr_b16 v[114:115], v127 offset:32
	ds_read_b64_tr_b16 v[116:117], v127 offset:1568
	ds_read_b64_tr_b16 v[122:123], v127 offset:64
	ds_read_b64_tr_b16 v[124:125], v127 offset:1600
	ds_read_b32 v0, v0
	s_waitcnt lgkmcnt(7)
	v_mfma_f32_16x16x32_bf16 v[118:121], v[118:121], v[18:21], v[132:135]
	s_nop 2
	ds_read_b128 v[132:135], v126
	s_waitcnt lgkmcnt(1)
	v_max_f32_e32 v0, v0, v0
	v_max_f32_e32 v0, v227, v0
	s_waitcnt lgkmcnt(0)
	v_sub_f32_e32 v1, v132, v0
	v_mul_f32_e32 v1, 0x3fb8aa3b, v1
	v_exp_f32_e32 v1, v1
	s_nop 0
	v_mul_f32_e32 v1, v118, v1
	v_sub_f32_e32 v118, v133, v0
	v_mul_f32_e32 v118, 0x3fb8aa3b, v118
	v_exp_f32_e32 v118, v118
	v_cndmask_b32_e64 v1, v1, 0, s[6:7]
	v_mul_f32_e32 v118, v119, v118
	v_sub_f32_e32 v119, v134, v0
	v_sub_f32_e32 v0, v135, v0
	v_mul_f32_e32 v119, 0x3fb8aa3b, v119
	v_mul_f32_e32 v0, 0x3fb8aa3b, v0
	v_exp_f32_e32 v119, v119
	v_exp_f32_e32 v0, v0
	v_cndmask_b32_e64 v118, 0, v118, s[8:9]
	v_cvt_pk_bf16_f32 v132, v1, v118
	v_mul_f32_e32 v119, v120, v119
	v_mul_f32_e32 v0, v121, v0
	v_cndmask_b32_e64 v119, v119, 0, s[10:11]
	v_cndmask_b32_e64 v0, v0, 0, s[12:13]
	v_cvt_pk_bf16_f32 v133, v119, v0
	v_mov_b32_e32 v134, v3
	v_mov_b32_e32 v135, v3
	s_nop 1
	v_mfma_f32_16x16x32_bf16 v[118:121], v[132:135], v[136:139], 0
	v_mfma_f32_16x16x32_bf16 v[114:117], v[132:135], v[114:117], 0
	v_mfma_f32_16x16x32_bf16 v[122:125], v[132:135], v[122:125], 0
.LBB0_662:
	s_andn2_b64 vcc, exec, s[0:1]
	s_cbranch_vccnz .LBB0_664
	s_nop 4
	ds_read_b128 v[114:117], v4 offset:8192
	ds_read_b128 v[118:121], v131 offset:8192
	ds_read_b128 v[122:125], v131
	s_waitcnt lgkmcnt(2)
	v_mfma_f32_16x16x32_bf16 v[110:113], v[110:113], v[38:41], 0
	v_add_u32_e32 v0, 0x23540, v128
	v_mfma_f32_16x16x32_bf16 v[38:41], v[114:117], v[38:41], 0
	ds_read_b128 v[114:117], v130 offset:8192
	ds_read_b128 v[132:135], v130
	s_waitcnt lgkmcnt(2)
	v_mfma_f32_16x16x32_bf16 v[110:113], v[122:125], v[34:37], v[110:113]
	v_mfma_f32_16x16x32_bf16 v[34:37], v[118:121], v[34:37], v[38:41]
	s_nop 3
	ds_read_b128 v[38:41], v129 offset:8192
	ds_read_b128 v[118:121], v129
	s_waitcnt lgkmcnt(2)
	v_mfma_f32_16x16x32_bf16 v[110:113], v[132:135], v[30:33], v[110:113]
	v_mfma_f32_16x16x32_bf16 v[30:33], v[114:117], v[30:33], v[34:37]
	s_nop 2
	ds_read_b128 v[34:37], v4 offset:8448
	ds_read_b128 v[114:117], v4 offset:256
	s_waitcnt lgkmcnt(2)
	v_mfma_f32_16x16x32_bf16 v[110:113], v[118:121], v[10:13], v[110:113]
	v_mfma_f32_16x16x32_bf16 v[10:13], v[38:41], v[10:13], v[30:33]
	s_nop 2
	ds_read_b128 v[30:33], v131 offset:8448
	ds_read_b128 v[38:41], v131 offset:256
	s_waitcnt lgkmcnt(2)
	v_mfma_f32_16x16x32_bf16 v[110:113], v[114:117], v[26:29], v[110:113]
	v_mfma_f32_16x16x32_bf16 v[10:13], v[34:37], v[26:29], v[10:13]
	ds_read_b128 v[26:29], v130 offset:8448
	ds_read_b128 v[34:37], v130 offset:256
	s_waitcnt lgkmcnt(2)
	v_mfma_f32_16x16x32_bf16 v[38:41], v[38:41], v[22:25], v[110:113]
	v_mfma_f32_16x16x32_bf16 v[10:13], v[30:33], v[22:25], v[10:13]
	ds_read_b128 v[22:25], v129 offset:256
	ds_read_b128 v[30:33], v129 offset:8448
	s_waitcnt lgkmcnt(2)
	v_mfma_f32_16x16x32_bf16 v[34:37], v[34:37], v[14:17], v[38:41]
	v_mfma_f32_16x16x32_bf16 v[10:13], v[26:29], v[14:17], v[10:13]
	s_waitcnt lgkmcnt(0)
	v_mfma_f32_16x16x32_bf16 v[22:25], v[22:25], v[18:21], v[34:37]
	v_mfma_f32_16x16x32_bf16 v[30:33], v[30:33], v[18:21], v[10:13]
	s_nop 0
	ds_read_b64_tr_b16 v[20:21], v127 offset:1536
	ds_read_b64_tr_b16 v[18:19], v127
	ds_read_b64_tr_b16 v[14:15], v127 offset:32
	ds_read_b64_tr_b16 v[16:17], v127 offset:1568
	s_nop 0
	ds_read_b64_tr_b16 v[10:11], v127 offset:64
	ds_read_b64_tr_b16 v[12:13], v127 offset:1600
	ds_read_b32 v0, v0
	ds_read_b128 v[26:29], v126
	s_waitcnt lgkmcnt(1)
	v_max_f32_e32 v0, v0, v0
	v_max_f32_e32 v38, v227, v0
	v_add_u32_e32 v0, 0x21540, v5
	ds_read_b128 v[34:37], v0
	s_waitcnt lgkmcnt(1)
	v_sub_f32_e32 v4, v29, v38
	v_mul_f32_e32 v4, 0x3fb8aa3b, v4
	v_exp_f32_e32 v5, v4
	v_sub_f32_e32 v4, v28, v38
	s_waitcnt lgkmcnt(0)
	v_sub_f32_e32 v0, v34, v38
	v_mul_f32_e32 v0, 0x3fb8aa3b, v0
	v_exp_f32_e32 v0, v0
	v_mul_f32_e32 v4, 0x3fb8aa3b, v4
	v_exp_f32_e32 v4, v4
	v_sub_f32_e32 v1, v37, v38
	v_mul_f32_e32 v0, v30, v0
	v_cndmask_b32_e64 v30, v0, 0, s[6:7]
	v_sub_f32_e32 v0, v35, v38
	v_mul_f32_e32 v0, 0x3fb8aa3b, v0
	v_exp_f32_e32 v0, v0
	v_mul_f32_e32 v1, 0x3fb8aa3b, v1
	v_pk_mul_f32 v[4:5], v[24:25], v[4:5]
	v_sub_f32_e32 v24, v27, v38
	v_mul_f32_e32 v0, v31, v0
	v_cndmask_b32_e64 v31, v0, 0, s[20:21]
	v_sub_f32_e32 v0, v36, v38
	v_mul_f32_e32 v0, 0x3fb8aa3b, v0
	v_exp_f32_e32 v0, v0
	v_exp_f32_e32 v1, v1
	v_mul_f32_e32 v24, 0x3fb8aa3b, v24
	v_exp_f32_e32 v25, v24
	v_sub_f32_e32 v24, v26, v38
	v_mul_f32_e32 v24, 0x3fb8aa3b, v24
	v_exp_f32_e32 v24, v24
	v_pk_mul_f32 v[0:1], v[32:33], v[0:1]
	v_pk_mul_f32 v[22:23], v[22:23], v[24:25]
	v_cvt_pk_bf16_f32 v0, v0, v1
	v_cndmask_b32_e64 v1, v0, 0, s[24:25]
	v_lshrrev_b32_e32 v0, 16, v0
	v_cndmask_b32_e64 v0, v0, 0, s[22:23]
	v_cvt_pk_bf16_f32 v22, v22, v23
	v_cvt_pk_bf16_f32 v23, v4, v5
	v_cvt_pk_bf16_f32 v24, v30, v31
	v_perm_b32 v25, v0, v1, s60
	s_nop 1
	v_mfma_f32_16x16x32_bf16 v[118:121], v[22:25], v[18:21], 0
	v_mfma_f32_16x16x32_bf16 v[114:117], v[22:25], v[14:17], 0
	v_mfma_f32_16x16x32_bf16 v[122:125], v[22:25], v[10:13], 0
; #define LAS __attribute__((address_space(3)))
; template <int SKIP>
; DEV void mlstm_phase(LAS char* shm, const bf16_t* q, const bf16_t* k, const bf16_t* v, const float* gpart, const float* b_ig, const float* b_fg, bf16_t* hc, const bool pre) {
;     ...
;             if (!(SKIP & 4)) {
;                 const float decay = __expf(m_prev - mxc);
; #pragma unroll
;                 for (int i = 0; i < 3; ++i)
; #pragma unroll
;                     for (int vt = 0; vt < 3; ++vt) cacc[i][vt] *= decay;
;                 const int q_ = fr >> 2, p_ = fr & 3;
;                 s16x4 wl[2][3], wh[2][3];
; #pragma unroll
;                 for (int kk = 0; kk < 2; ++kk)
; #pragma unroll
;                     for (int vt = 0; vt < 3; ++vt) {
;                         wl[kk][vt] = __builtin_amdgcn_ds_read_tr16_b64_v4i16((LAS s16x4*)(shm + VWT + (32 * kk + 8 * fq + q_) * VRS + (16 * vt + 4 * p_) * 2));
;                         wh[kk][vt] = __builtin_amdgcn_ds_read_tr16_b64_v4i16((LAS s16x4*)(shm + VWT + (32 * kk + 8 * fq + 4 + q_) * VRS + (16 * vt + 4 * p_) * 2));
;                     }
;                 bf16x8 bfv[2][3];
; #pragma unroll
;                 for (int kk = 0; kk < 2; ++kk)
; #pragma unroll
;                     for (int vt = 0; vt < 3; ++vt) { bfv[kk][vt][0] = wl[kk][vt][0]; bfv[kk][vt][1] = wl[kk][vt][1]; bfv[kk][vt][2] = wl[kk][vt][2]; bfv[kk][vt][3] = wl[kk][vt][3];
;                         bfv[kk][vt][4] = wh[kk][vt][0]; bfv[kk][vt][5] = wh[kk][vt][1]; bfv[kk][vt][6] = wh[kk][vt][2]; bfv[kk][vt][7] = wh[kk][vt][3]; }
;                 const int rl_ = 8 * fq + q_, rh_ = rl_ + 4;
; #pragma unroll
;                 for (int i = 0; i < 3; ++i) {
;                     if (i < ndt) {
;                         const int un = 2 * (dt0 + i) + (p_ >> 1);
;                         s16x4 kl[2], kh[2];
; #pragma unroll
;                         for (int kk = 0; kk < 2; ++kk) {
;                             kl[kk] = __builtin_amdgcn_ds_read_tr16_b64_v4i16((LAS s16x4*)(kbuf + (32 * kk + rl_) * 512 + ((un ^ (rl_ & 15)) << 4) + (p_ & 1) * 8));
;                             kh[kk] = __builtin_amdgcn_ds_read_tr16_b64_v4i16((LAS s16x4*)(kbuf + (32 * kk + rh_) * 512 + ((un ^ (rh_ & 15)) << 4) + (p_ & 1) * 8));
;                         }
; #pragma unroll
;                         for (int kk = 0; kk < 2; ++kk) {
.LBB0_664:
	v_mov_b32_e32 v0, s43
	v_sub_f32_e32 v0, s28, v0
	v_mul_f32_e32 v0, 0x3fb8aa3b, v0
	v_exp_f32_e32 v4, v0
	v_add_u32_e32 v34, s29, v190
	v_add_u32_e32 v0, v34, v220
	v_add3_u32 v1, v34, v167, v193
	v_pk_mul_f32 v[68:69], v[68:69], v[4:5] op_sel_hi:[1,0]
	v_pk_mul_f32 v[66:67], v[66:67], v[4:5] op_sel_hi:[1,0]
	v_pk_mul_f32 v[64:65], v[64:65], v[4:5] op_sel_hi:[1,0]
	v_add_u32_e32 v5, v0, v194
	s_nop 0
	ds_read_b64_tr_b16 v[22:23], v1
	ds_read_b64_tr_b16 v[24:25], v5
	ds_read_b64_tr_b16 v[28:29], v210 offset:384
	ds_read_b64_tr_b16 v[26:27], v210
	ds_read_b64_tr_b16 v[30:31], v210 offset:32
	ds_read_b64_tr_b16 v[18:19], v210 offset:64
	v_pk_mul_f32 v[12:13], v[52:53], v[4:5] op_sel_hi:[1,0]
	v_pk_mul_f32 v[10:11], v[50:51], v[4:5] op_sel_hi:[1,0]
	v_add_u32_e32 v0, v0, v193
	ds_read_b64_tr_b16 v[38:39], v0 offset:18432
	ds_read_b64_tr_b16 v[36:37], v1 offset:16384
	s_waitcnt lgkmcnt(0)
	v_mfma_f32_16x16x32_bf16 v[50:53], v[22:25], v[26:29], v[10:13]
	ds_read_b64_tr_b16 v[32:33], v210 offset:416
	ds_read_b64_tr_b16 v[20:21], v210 offset:448
	ds_read_b64_tr_b16 v[14:15], v210 offset:3072
	ds_read_b64_tr_b16 v[10:11], v210 offset:3104
	v_pk_mul_f32 v[48:49], v[48:49], v[4:5] op_sel_hi:[1,0]
	v_pk_mul_f32 v[46:47], v[46:47], v[4:5] op_sel_hi:[1,0]
	v_pk_mul_f32 v[44:45], v[44:45], v[4:5] op_sel_hi:[1,0]
	v_pk_mul_f32 v[42:43], v[42:43], v[4:5] op_sel_hi:[1,0]
	s_waitcnt lgkmcnt(3)
	v_mfma_f32_16x16x32_bf16 v[46:49], v[22:25], v[30:33], v[46:49]
	ds_read_b64_tr_b16 v[16:17], v210 offset:3456
	v_cndmask_b32_e64 v0, 0, 1, s[34:35]
	v_pk_mul_f32 v[62:63], v[62:63], v[4:5] op_sel_hi:[1,0]
	s_waitcnt lgkmcnt(3)
	v_mfma_f32_16x16x32_bf16 v[40:43], v[22:25], v[18:21], v[42:45]
	ds_read_b64_tr_b16 v[12:13], v210 offset:3488
	ds_read_b64_tr_b16 v[24:25], v210 offset:3520
	ds_read_b64_tr_b16 v[22:23], v210 offset:3136
	v_pk_mul_f32 v[56:57], v[56:57], v[4:5] op_sel_hi:[1,0]
	v_pk_mul_f32 v[54:55], v[54:55], v[4:5] op_sel_hi:[1,0]
	s_waitcnt lgkmcnt(3)
	v_mfma_f32_16x16x32_bf16 v[50:53], v[36:39], v[14:17], v[50:53]
	v_cmp_ne_u32_e64 s[28:29], 1, v0
	s_andn2_b64 vcc, exec, s[34:35]
	s_waitcnt lgkmcnt(2)
	v_mfma_f32_16x16x32_bf16 v[46:49], v[36:39], v[10:13], v[46:49]
	s_waitcnt lgkmcnt(0)
	v_mfma_f32_16x16x32_bf16 v[42:45], v[36:39], v[22:25], v[40:43]
	s_cbranch_vccnz .LBB0_666
	v_add_u32_e32 v0, v34, v222
	v_add3_u32 v1, v34, v221, v193
	v_add_u32_e32 v5, v0, v194
	v_add_u32_e32 v0, v0, v193
	ds_read_b64_tr_b16 v[36:37], v1
	ds_read_b64_tr_b16 v[38:39], v5
	ds_read_b64_tr_b16 v[110:111], v1 offset:16384
	ds_read_b64_tr_b16 v[112:113], v0 offset:18432
	s_waitcnt lgkmcnt(2)
	v_mfma_f32_16x16x32_bf16 v[66:69], v[36:39], v[26:29], v[66:69]
	v_mfma_f32_16x16x32_bf16 v[62:65], v[36:39], v[30:33], v[62:65]
	v_mfma_f32_16x16x32_bf16 v[36:39], v[36:39], v[18:21], v[54:57]
	s_waitcnt lgkmcnt(0)
	v_mfma_f32_16x16x32_bf16 v[66:69], v[110:113], v[14:17], v[66:69]
	v_mfma_f32_16x16x32_bf16 v[62:65], v[110:113], v[10:13], v[62:65]
	v_mfma_f32_16x16x32_bf16 v[54:57], v[110:113], v[22:25], v[36:39]

; DEV int opaque_tid() { int t = threadIdx.x; asm volatile("" : "+v"(t)); return t; }
; #define LAS __attribute__((address_space(3)))
; DEV unsigned xb_ld(unsigned* p) { return __hip_atomic_load(p, __ATOMIC_RELAXED, __HIP_MEMORY_SCOPE_AGENT); }
; DEV unsigned xb_add(unsigned* p, unsigned v) { return __hip_atomic_fetch_add(p, v, __ATOMIC_RELAXED, __HIP_MEMORY_SCOPE_AGENT); }
; DEV unsigned xb_xcc_id() { return (unsigned)__builtin_amdgcn_s_getreg((3 << 11) | 20) & 0xFu; }
; #define XB_SPIN(cond, bar) do { unsigned _sp = 0; while (cond) { __builtin_amdgcn_s_sleep(1); \
;     if ((++_sp & 255u) == 0u) { if (xb_ld(&(bar)[XB_TMO])) break; if (_sp > XB_SPIN_CAP) { atomicAdd(&(bar)[XB_TMO], 1u); break; } } } } while (0)
; DEV void xcd_wait_lds(LAS char* lds) {
;     volatile LAS unsigned* st = (volatile LAS unsigned*)(lds + LDS_BYTES - 16);
;     const int tid_ = opaque_tid();
;     if (tid_ == 64) asm volatile("buffer_inv sc1\n\ts_waitcnt vmcnt(0)" ::: "memory");
;     if (tid_ == 0) {
;         unsigned* bar = (unsigned*)((char*)ldptr(lds, 30) + SLOTS * 7 + BAR_OFF);
;         const unsigned x = xb_xcc_id();
;         const unsigned mode = st[2], val = st[3];
;         if (mode != 3u) XB_SPIN(xb_ld(&bar[XB_TOPGEN]) <= val, bar);
;         if (mode == 2u) xb_add(&bar[XB_XGEN(x)], 1u);
;         asm volatile("s_waitcnt vmcnt(0)" ::: "memory");
;     }
;     asm volatile("s_waitcnt lgkmcnt(0)\n\ts_barrier" ::: "memory");
;     if (tid_ == 0) st[2] = 0u;
.LBB0_725:
	s_and_b32 s41, s31, 0xff
	s_mov_b64 s[84:85], -1
	s_cmp_lg_u32 s41, 0
	s_mov_b64 s[88:89], -1
	s_sleep 3
	s_cbranch_scc0 .LBB0_728
	s_and_b64 vcc, exec, s[88:89]
	s_cbranch_vccz .LBB0_724

.LBB0_766:
	global_load_dword v0, v137, s[42:43] sc1
	s_mov_b64 s[0:1], -1
	s_mov_b64 s[80:81], -1
	s_waitcnt vmcnt(0)
	v_cmp_lt_u32_e32 vcc, 1, v0
	s_cbranch_vccnz .LBB0_765
	s_sleep 3
	global_load_dword v0, v137, s[42:43] sc1
	s_waitcnt vmcnt(0)
	v_cmp_gt_u32_e32 vcc, 2, v0
	s_cbranch_vccz .LBB0_765
	s_sleep 3
	global_load_dword v0, v137, s[42:43] sc1
	s_waitcnt vmcnt(0)
	v_cmp_gt_u32_e32 vcc, 2, v0
	s_cbranch_vccz .LBB0_765
	s_sleep 3
	global_load_dword v0, v137, s[42:43] sc1
	s_waitcnt vmcnt(0)
	v_cmp_gt_u32_e32 vcc, 2, v0
	s_cbranch_vccz .LBB0_765
	s_sleep 3
	global_load_dword v0, v137, s[42:43] sc1
	s_waitcnt vmcnt(0)
	v_cmp_gt_u32_e32 vcc, 2, v0
	s_cbranch_vccz .LBB0_765
	s_add_i32 s2, s2, -5
	s_cmp_eq_u32 s2, 0
	s_mov_b64 s[0:1], 0
	s_cselect_b64 s[80:81], -1, 0
	s_sleep 3
	s_branch .LBB0_765

.LBB0_885:
	global_load_dword v0, v218, s[42:43] sc1
	s_mov_b64 s[0:1], -1
	s_mov_b64 s[82:83], -1
	s_waitcnt vmcnt(0)
	v_cmp_lt_u32_e32 vcc, 3, v0
	s_cbranch_vccnz .LBB0_884
	s_sleep 3
	global_load_dword v0, v218, s[42:43] sc1
	s_waitcnt vmcnt(0)
	v_cmp_gt_u32_e32 vcc, 4, v0
	s_cbranch_vccz .LBB0_884
	s_sleep 3
	global_load_dword v0, v218, s[42:43] sc1
	s_waitcnt vmcnt(0)
	v_cmp_gt_u32_e32 vcc, 4, v0
	s_cbranch_vccz .LBB0_884
	s_sleep 3
	global_load_dword v0, v218, s[42:43] sc1
	s_waitcnt vmcnt(0)
	v_cmp_gt_u32_e32 vcc, 4, v0
	s_cbranch_vccz .LBB0_884
	s_sleep 3
	global_load_dword v0, v218, s[42:43] sc1
	s_waitcnt vmcnt(0)
	v_cmp_gt_u32_e32 vcc, 4, v0
	s_cbranch_vccz .LBB0_884
	s_add_i32 s12, s12, -5
	s_cmp_eq_u32 s12, 0
	s_mov_b64 s[0:1], 0
	s_cselect_b64 s[82:83], -1, 0
	s_sleep 3
	s_branch .LBB0_884

.LBB0_1353:
	global_load_dword v0, v100, s[10:11] sc1
	s_mov_b64 s[0:1], -1
	s_mov_b64 s[12:13], -1
	s_waitcnt vmcnt(0)
	v_cmp_lt_u32_e32 vcc, 3, v0
	s_cbranch_vccnz .LBB0_1352
	s_sleep 3
	global_load_dword v0, v100, s[10:11] sc1
	s_waitcnt vmcnt(0)
	v_cmp_gt_u32_e32 vcc, 4, v0
	s_cbranch_vccz .LBB0_1352
	s_sleep 3
	global_load_dword v0, v100, s[10:11] sc1
	s_waitcnt vmcnt(0)
	v_cmp_gt_u32_e32 vcc, 4, v0
	s_cbranch_vccz .LBB0_1352
	s_sleep 3
	global_load_dword v0, v100, s[10:11] sc1
	s_waitcnt vmcnt(0)
	v_cmp_gt_u32_e32 vcc, 4, v0
	s_cbranch_vccz .LBB0_1352
	s_sleep 3
	global_load_dword v0, v100, s[10:11] sc1
	s_waitcnt vmcnt(0)
	v_cmp_gt_u32_e32 vcc, 4, v0
	s_cbranch_vccz .LBB0_1352
	s_add_i32 s2, s2, -5
	s_cmp_eq_u32 s2, 0
	s_mov_b64 s[0:1], 0
	s_cselect_b64 s[12:13], -1, 0
	s_sleep 3
	s_branch .LBB0_1352

; template <int SKIP>
; DEV void mlstm_phase(LAS char* shm, const bf16_t* q, const bf16_t* k, const bf16_t* v, const float* gpart, const float* b_ig, const float* b_fg, bf16_t* hc, const bool pre) {
;     ...
;             if (wid < 4) asm volatile("s_waitcnt vmcnt(1)" ::: "memory");
;             else asm volatile("s_waitcnt vmcnt(0)" ::: "memory");
;     ...
;             m_prev = __int_as_float(__builtin_amdgcn_readfirstlane(__float_as_int(btot + mxc)));
; #pragma unroll
;             for (int ks = 0; ks < 8; ++ks) qfr[ks] = qnx[ks];
.LBB0_1486:
	s_and_b64 vcc, exec, s[70:71]
	s_cbranch_vccnz .Lml1_w47
	s_waitcnt vmcnt(1)
	s_branch .Lml1_go
.Lml1_w47:
	s_waitcnt vmcnt(0)
.Lml1_go:
	s_addk_i32 s40, 0x100
	v_mov_b32_e32 v0, s42
	s_add_u32 s38, s38, 0x8000
	v_add_f32_e32 v0, s43, v0
	s_addc_u32 s39, s39, 0
	s_add_i32 s41, s41, 8
	v_mov_b64_e32 v[38:39], v[98:99]
	v_mov_b64_e32 v[34:35], v[90:91]
	v_mov_b64_e32 v[30:31], v[82:83]
	v_mov_b64_e32 v[10:11], v[78:79]
	v_mov_b64_e32 v[26:27], v[106:107]
	v_mov_b64_e32 v[22:23], v[102:103]
	v_mov_b64_e32 v[14:15], v[94:95]
	v_mov_b64_e32 v[18:19], v[86:87]
	v_readfirstlane_b32 s28, v0
	v_lshl_add_u64 v[168:169], v[168:169], 0, s[84:85]
	v_lshl_add_u64 v[172:173], v[172:173], 0, s[84:85]
	v_lshl_add_u64 v[174:175], v[174:175], 0, s[84:85]
	s_cmp_eq_u32 s40, 0
	v_mov_b64_e32 v[40:41], v[100:101]
	v_mov_b64_e32 v[36:37], v[92:93]
	v_mov_b64_e32 v[32:33], v[84:85]
	v_mov_b64_e32 v[12:13], v[80:81]
	v_mov_b64_e32 v[28:29], v[108:109]
	v_mov_b64_e32 v[24:25], v[104:105]
	v_mov_b64_e32 v[16:17], v[96:97]
	v_mov_b64_e32 v[20:21], v[88:89]
	s_cbranch_scc1 .LBB0_1445

; #define LAS __attribute__((address_space(3)))
; #define MLK_ISSUE(chunk_off_elems, buf) do { const char* kg_ = (const char*)(k + (chunk_off_elems)); _Pragma("unroll") for (int i_ = 0; i_ < 4; ++i_) \
;             __builtin_amdgcn_global_load_lds((const unsigned*)(kg_ + kvoff + (size_t)i_ * 16 * DM * 2), (LAS unsigned*)(shm + (buf) * 32768 + (i_ * 8 + wid) * 1024), 16, 0, 0); } while (0)
; DEV void mlstm_b_wave(LAS char* shm, const bf16x8 (&qfr)[8], int fr, int fq, f32x4 (&nacc)[3]) {
;     constexpr int CB = 81408, RS = 528;
;     const LAS char* cbp = shm + CB + fr * RS + fq * 16;
;     bf16x8 cf[3];
; #pragma unroll
;     for (int vt = 0; vt < 3; ++vt) cf[vt] = *(const LAS bf16x8*)(cbp + vt * 16 * RS);
; #pragma unroll
;     for (int ks = 0; ks < 8; ++ks) {
;         bf16x8 cn[3] = {cf[0], cf[1], cf[2]};
;         if (ks < 7) {
; #pragma unroll
;             for (int vt = 0; vt < 3; ++vt) cn[vt] = *(const LAS bf16x8*)(cbp + vt * 16 * RS + (ks + 1) * 64);
;         }
; #pragma unroll
;         for (int vt = 0; vt < 3; ++vt) nacc[vt] = __builtin_amdgcn_mfma_f32_16x16x32_bf16(qfr[ks], cf[vt], nacc[vt], 0, 0, 0);
; #pragma unroll
;         for (int vt = 0; vt < 3; ++vt) cf[vt] = cn[vt];
;     }
; }
; template <int SKIP>
; DEV void mlstm_phase(LAS char* shm, const bf16_t* q, const bf16_t* k, const bf16_t* v, const float* gpart, const float* b_ig, const float* b_fg, bf16_t* hc, const bool pre) {
;     ...
;             if (j + 1 < SEQ / CHUNK) {
;                 const size_t cn = cb + (size_t)CHUNK * DM;
;                 MLK_ISSUE(cn, (j + 1) & 1);
; #pragma unroll
;                 for (int ks = 0; ks < 8; ++ks) qnx[ks] = *(const bf16x8*)(qfb + (size_t)(j + 1) * 16384 + ks * 512);
;                 if (wid < 4) vv = *(const uint4*)(v + cn + (size_t)(tid >> 2) * DM + vs * 32 + (tid & 3) * 8);
;             }
.LBB0_1501:
	s_waitcnt lgkmcnt(0)
	s_barrier
	s_and_b64 vcc, exec, s[70:71]
	s_cbranch_vccnz .Lpf1_done
	s_cmpk_eq_i32 s40, 0xff00
	s_cbranch_scc1 .Lpf1_done
	v_lshl_add_u64 v[0:1], v[168:169], 0, s[64:65]
	s_mov_b64 s[0:1], 0x2032000
	v_lshl_add_u64 v[4:5], v[0:1], 0, s[0:1]
	s_add_i32 s0, s38, 0x8000
	s_and_b32 s0, s0, 0x8000
	s_add_i32 s29, s59, s0
	s_mov_b32 m0, s29
	s_mov_b64 s[0:1], 0x203a000
	global_load_lds_dwordx4 v[4:5], off
	v_lshl_add_u64 v[4:5], v[0:1], 0, s[0:1]
	s_add_i32 m0, s29, 0x2000
	s_mov_b64 s[0:1], 0x2042000
	global_load_lds_dwordx4 v[4:5], off
	v_lshl_add_u64 v[4:5], v[0:1], 0, s[0:1]
	s_add_i32 m0, s29, 0x4000
	s_mov_b64 s[0:1], 0x204a000
	global_load_lds_dwordx4 v[4:5], off
	v_lshl_add_u64 v[0:1], v[0:1], 0, s[0:1]
	s_add_i32 m0, s29, 0x6000
	s_mov_b32 s0, 0xc074000
	global_load_lds_dwordx4 v[0:1], off
	v_lshl_add_u64 v[0:1], v[170:171], 0, s[38:39]
	v_add_co_u32_e32 v4, vcc, s0, v0
	s_nop 1
	v_addc_co_u32_e32 v5, vcc, 0, v1, vcc
	v_add_co_u32_e32 v0, vcc, 0xc075000, v0
	global_load_dwordx4 v[98:101], v[4:5], off
	global_load_dwordx4 v[90:93], v[4:5], off offset:1024
	global_load_dwordx4 v[82:85], v[4:5], off offset:2048
	global_load_dwordx4 v[78:81], v[4:5], off offset:3072
	v_addc_co_u32_e32 v1, vcc, 0, v1, vcc
	global_load_dwordx4 v[106:109], v[0:1], off
	global_load_dwordx4 v[102:105], v[0:1], off offset:1024
	global_load_dwordx4 v[94:97], v[0:1], off offset:2048
	global_load_dwordx4 v[86:89], v[0:1], off offset:3072
	v_lshl_add_u64 v[0:1], v[174:175], 0, s[64:65]
	v_add_co_u32_e32 v0, vcc, 0xa07a000, v0
	s_nop 1
	v_addc_co_u32_e32 v1, vcc, 0, v1, vcc
	global_load_dwordx4 v[6:9], v[0:1], off
.Lpf1_done:
	v_add_u32_e32 v2, s40, v204
	s_mov_b64 s[0:1], -1
	s_and_b64 vcc, exec, s[70:71]
	v_add_u32_e32 v228, 0x23500, v2
	s_cbranch_vccz .LBB0_1503
	ds_read_b128 v[110:113], v209
	ds_read_b128 v[114:117], v209 offset:8448
	ds_read_b128 v[118:121], v209 offset:16896
	ds_read_b128 v[122:125], v209 offset:64
	ds_read_b128 v[126:129], v209 offset:8512
	ds_read_b128 v[130:133], v209 offset:16960
	s_waitcnt lgkmcnt(3)
	v_mfma_f32_16x16x32_bf16 v[110:113], v[38:41], v[110:113], 0
	ds_read_b128 v[134:137], v209 offset:128
	ds_read_b128 v[138:141], v209 offset:8576
	ds_read_b128 v[142:145], v209 offset:17024
	s_mov_b64 s[0:1], 0
	v_mfma_f32_16x16x32_bf16 v[114:117], v[38:41], v[114:117], 0
	v_mfma_f32_16x16x32_bf16 v[118:121], v[38:41], v[118:121], 0
	s_waitcnt lgkmcnt(3)
	v_mfma_f32_16x16x32_bf16 v[110:113], v[34:37], v[122:125], v[110:113]
	v_mfma_f32_16x16x32_bf16 v[114:117], v[34:37], v[126:129], v[114:117]
	v_mfma_f32_16x16x32_bf16 v[118:121], v[34:37], v[130:133], v[118:121]
	ds_read_b128 v[122:125], v209 offset:192
	ds_read_b128 v[126:129], v209 offset:8640
	ds_read_b128 v[130:133], v209 offset:17088
	s_waitcnt lgkmcnt(3)
	v_mfma_f32_16x16x32_bf16 v[110:113], v[30:33], v[134:137], v[110:113]
	v_mfma_f32_16x16x32_bf16 v[114:117], v[30:33], v[138:141], v[114:117]
	v_mfma_f32_16x16x32_bf16 v[118:121], v[30:33], v[142:145], v[118:121]
	ds_read_b128 v[134:137], v209 offset:256
	ds_read_b128 v[138:141], v209 offset:8704
	ds_read_b128 v[142:145], v209 offset:17152
	s_waitcnt lgkmcnt(3)
	v_mfma_f32_16x16x32_bf16 v[110:113], v[10:13], v[122:125], v[110:113]
	v_mfma_f32_16x16x32_bf16 v[114:117], v[10:13], v[126:129], v[114:117]
	v_mfma_f32_16x16x32_bf16 v[118:121], v[10:13], v[130:133], v[118:121]
	ds_read_b128 v[122:125], v209 offset:320
	ds_read_b128 v[126:129], v209 offset:8768
	ds_read_b128 v[130:133], v209 offset:17216
	s_waitcnt lgkmcnt(3)
	v_mfma_f32_16x16x32_bf16 v[110:113], v[26:29], v[134:137], v[110:113]
	v_mfma_f32_16x16x32_bf16 v[114:117], v[26:29], v[138:141], v[114:117]
	v_mfma_f32_16x16x32_bf16 v[118:121], v[26:29], v[142:145], v[118:121]
	ds_read_b128 v[134:137], v209 offset:384
	ds_read_b128 v[138:141], v209 offset:8832
	ds_read_b128 v[142:145], v209 offset:17280
	s_waitcnt lgkmcnt(3)
	v_mfma_f32_16x16x32_bf16 v[110:113], v[22:25], v[122:125], v[110:113]
	v_mfma_f32_16x16x32_bf16 v[114:117], v[22:25], v[126:129], v[114:117]
	v_mfma_f32_16x16x32_bf16 v[118:121], v[22:25], v[130:133], v[118:121]
	ds_read_b128 v[122:125], v209 offset:17344
	ds_read_b128 v[126:129], v209 offset:448
	ds_read_b128 v[130:133], v209 offset:8896
	s_waitcnt lgkmcnt(0)
	v_mfma_f32_16x16x32_bf16 v[110:113], v[14:17], v[134:137], v[110:113]
	v_mfma_f32_16x16x32_bf16 v[134:137], v[14:17], v[142:145], v[118:121]
	v_mfma_f32_16x16x32_bf16 v[118:121], v[18:21], v[126:129], v[110:113]
	s_nop 5
	ds_read_b128 v[110:113], v228
	v_mfma_f32_16x16x32_bf16 v[114:117], v[14:17], v[138:141], v[114:117]
	s_waitcnt lgkmcnt(0)
	v_max_f32_e32 v0, v110, v110
	v_max_f32_e32 v4, v111, v111
	v_max_f32_e32 v0, v227, v0
	v_max_f32_e32 v4, v227, v4
	v_sub_f32_e32 v0, s28, v0
	v_sub_f32_e32 v4, s28, v4
	v_max_f32_e32 v110, v112, v112
	v_max_f32_e32 v112, v113, v113
	v_mul_f32_e32 v0, 0x3fb8aa3b, v0
	v_mul_f32_e32 v4, 0x3fb8aa3b, v4
	v_max_f32_e32 v110, v227, v110
	v_max_f32_e32 v112, v227, v112
	v_mfma_f32_16x16x32_bf16 v[114:117], v[18:21], v[130:133], v[114:117]
	v_exp_f32_e32 v0, v0
	v_exp_f32_e32 v4, v4
	v_sub_f32_e32 v110, s28, v110
	v_mfma_f32_16x16x32_bf16 v[122:125], v[18:21], v[122:125], v[134:137]
	v_sub_f32_e32 v112, s28, v112
	v_mul_f32_e32 v110, 0x3fb8aa3b, v110
	v_mul_f32_e32 v112, 0x3fb8aa3b, v112
	v_exp_f32_e32 v110, v110
	v_exp_f32_e32 v112, v112
	v_mul_f32_e32 v1, v118, v0
	v_mul_f32_e32 v5, v119, v4
	v_mul_f32_e32 v126, v114, v0
	v_mul_f32_e32 v0, v122, v0
	ds_write2_b32 v219, v1, v126 offset1:16
	v_mul_f32_e32 v1, v115, v4
	ds_write2_b32 v219, v0, v5 offset0:32 offset1:52
	v_mul_f32_e32 v0, v123, v4
	v_mul_f32_e32 v111, v120, v110
	v_mul_f32_e32 v113, v121, v112
	v_mul_f32_e32 v126, v116, v110
	ds_write2_b32 v219, v1, v0 offset0:68 offset1:84
	v_mul_f32_e32 v0, v124, v110
	ds_write2_b32 v219, v111, v126 offset0:104 offset1:120
	v_mul_f32_e32 v111, v117, v112
	ds_write2_b32 v219, v0, v113 offset0:136 offset1:156
	v_mul_f32_e32 v0, v125, v112
	ds_write2_b32 v219, v111, v0 offset0:172 offset1:188
; #define LAS __attribute__((address_space(3)))
; template <int TT>
; DEV void mlstm_a_wave(LAS char* shm, const LAS char* kbuf, const bf16x8 (&qfr)[8], int fr, int fq, float m_prev, const LAS float* tpj, const LAS float* taj, f32x4 (&nacc)[3]) {
;     ...
;     for (int jj = 0; jj < NT; ++jj) kf[jj] = *(const LAS bf16x8*)MLK_ADDR(jj, 0);
; #pragma unroll
;     for (int ks = 0; ks < 8; ++ks) {
;         bf16x8 kn[NT];
; #pragma unroll
;         for (int jj = 0; jj < NT; ++jj) kn[jj] = kf[jj];
;         if (ks < 7) {
; #pragma unroll
;             for (int jj = 0; jj < NT; ++jj) kn[jj] = *(const LAS bf16x8*)MLK_ADDR(jj, ks + 1);
;         }
; #pragma unroll
;         for (int jj = 0; jj < NT; ++jj) sacc[jj] = __builtin_amdgcn_mfma_f32_16x16x32_bf16(kf[jj], qfr[ks], sacc[jj], 0, 0, 0);
; #pragma unroll
;         for (int jj = 0; jj < NT; ++jj) kf[jj] = kn[jj];
;     }
; template <int SKIP>
; DEV void mlstm_phase(LAS char* shm, const bf16_t* q, const bf16_t* k, const bf16_t* v, const float* gpart, const float* b_ig, const float* b_fg, bf16_t* hc, const bool pre) {
;     ...
;             if (wid < 4) { if (!(SKIP & 1)) {
;                 const LAS float* tpj = tp + j * 64; const LAS float* taj = ta + j * 64;
;                 if (tt == 0) mlstm_a_wave<0>(shm, kbuf, qfr, fr, fq, m_prev, tpj, taj, nacc);
;                 else if (tt == 1) mlstm_a_wave<1>(shm, kbuf, qfr, fr, fq, m_prev, tpj, taj, nacc);
;                 else if (tt == 2) mlstm_a_wave<2>(shm, kbuf, qfr, fr, fq, m_prev, tpj, taj, nacc);
;                 else mlstm_a_wave<3>(shm, kbuf, qfr, fr, fq, m_prev, tpj, taj, nacc);
.LBB0_1503:
	s_and_b32 s29, s38, 0x8000
	s_andn2_b64 vcc, exec, s[0:1]
	s_add_i32 s29, s29, 0
	s_cbranch_vccnz .LBB0_1515
	v_add3_u32 v5, s29, v180, v181
	v_add_u32_e32 v4, v5, v182
	ds_read_b128 v[110:113], v4
	s_cmp_lt_i32 s61, 2
	s_mov_b64 s[0:1], -1
	s_cbranch_scc1 .LBB0_1510
	s_cmp_gt_i32 s61, 2
	s_cbranch_scc0 .LBB0_1507
	ds_read_b128 v[114:117], v4 offset:8192
	ds_read_b128 v[118:121], v4 offset:16384
	ds_read_b128 v[122:125], v4 offset:24576
	v_add_u32_e32 v0, v5, v183
	ds_read_b128 v[126:129], v0
	ds_read_b128 v[130:133], v0 offset:8192
	ds_read_b128 v[134:137], v0 offset:16384
	ds_read_b128 v[138:141], v0 offset:24576
	s_waitcnt lgkmcnt(4)
	v_mfma_f32_16x16x32_bf16 v[142:145], v[110:113], v[38:41], 0
	v_add_u32_e32 v1, v5, v184
	ds_read_b128 v[146:149], v1
	ds_read_b128 v[150:153], v1 offset:8192
	ds_read_b128 v[230:233], v1 offset:16384
	ds_read_b128 v[234:237], v1 offset:24576
	v_add_u32_e32 v229, v5, v185
	v_mfma_f32_16x16x32_bf16 v[114:117], v[114:117], v[38:41], 0
	s_mov_b64 s[0:1], 0
	v_mfma_f32_16x16x32_bf16 v[118:121], v[118:121], v[38:41], 0
	v_mfma_f32_16x16x32_bf16 v[122:125], v[122:125], v[38:41], 0
	s_waitcnt lgkmcnt(4)
	v_mfma_f32_16x16x32_bf16 v[126:129], v[126:129], v[34:37], v[142:145]
	v_mfma_f32_16x16x32_bf16 v[114:117], v[130:133], v[34:37], v[114:117]
	v_mfma_f32_16x16x32_bf16 v[118:121], v[134:137], v[34:37], v[118:121]
	v_mfma_f32_16x16x32_bf16 v[122:125], v[138:141], v[34:37], v[122:125]
	ds_read_b128 v[130:133], v229
	ds_read_b128 v[134:137], v229 offset:8192
	ds_read_b128 v[138:141], v229 offset:16384
	ds_read_b128 v[142:145], v229 offset:24576
	s_waitcnt lgkmcnt(4)
	v_mfma_f32_16x16x32_bf16 v[126:129], v[146:149], v[30:33], v[126:129]
	v_mfma_f32_16x16x32_bf16 v[114:117], v[150:153], v[30:33], v[114:117]
	v_mfma_f32_16x16x32_bf16 v[118:121], v[230:233], v[30:33], v[118:121]
	v_mfma_f32_16x16x32_bf16 v[122:125], v[234:237], v[30:33], v[122:125]
	ds_read_b128 v[146:149], v4 offset:256
	ds_read_b128 v[150:153], v4 offset:8448
	ds_read_b128 v[230:233], v4 offset:16640
	ds_read_b128 v[234:237], v4 offset:24832
	s_waitcnt lgkmcnt(4)
	v_mfma_f32_16x16x32_bf16 v[126:129], v[130:133], v[10:13], v[126:129]
	v_mfma_f32_16x16x32_bf16 v[114:117], v[134:137], v[10:13], v[114:117]
	v_mfma_f32_16x16x32_bf16 v[118:121], v[138:141], v[10:13], v[118:121]
	v_mfma_f32_16x16x32_bf16 v[122:125], v[142:145], v[10:13], v[122:125]
	ds_read_b128 v[130:133], v0 offset:256
	ds_read_b128 v[134:137], v0 offset:8448
	ds_read_b128 v[138:141], v0 offset:16640
	ds_read_b128 v[142:145], v0 offset:24832
	v_add_u32_e32 v0, v187, v186
	s_waitcnt lgkmcnt(4)
	v_mfma_f32_16x16x32_bf16 v[126:129], v[146:149], v[26:29], v[126:129]
	v_mfma_f32_16x16x32_bf16 v[114:117], v[150:153], v[26:29], v[114:117]
	v_mfma_f32_16x16x32_bf16 v[118:121], v[230:233], v[26:29], v[118:121]
	v_mfma_f32_16x16x32_bf16 v[122:125], v[234:237], v[26:29], v[122:125]
	ds_read_b128 v[146:149], v1 offset:256
	ds_read_b128 v[150:153], v1 offset:8448
	ds_read_b128 v[230:233], v1 offset:16640
	ds_read_b128 v[234:237], v1 offset:24832
	s_waitcnt lgkmcnt(4)
	v_mfma_f32_16x16x32_bf16 v[126:129], v[130:133], v[22:25], v[126:129]
	v_mfma_f32_16x16x32_bf16 v[114:117], v[134:137], v[22:25], v[114:117]
	v_mfma_f32_16x16x32_bf16 v[118:121], v[138:141], v[22:25], v[118:121]
	ds_read_b128 v[130:133], v229 offset:256
	ds_read_b128 v[134:137], v229 offset:8448
	ds_read_b128 v[138:141], v229 offset:16640
	ds_read_b128 v[238:241], v229 offset:24832
	v_mfma_f32_16x16x32_bf16 v[122:125], v[142:145], v[22:25], v[122:125]
	s_waitcnt lgkmcnt(4)
	v_mfma_f32_16x16x32_bf16 v[126:129], v[146:149], v[14:17], v[126:129]
	v_mfma_f32_16x16x32_bf16 v[114:117], v[150:153], v[14:17], v[114:117]
	v_mfma_f32_16x16x32_bf16 v[118:121], v[230:233], v[14:17], v[118:121]
	v_mfma_f32_16x16x32_bf16 v[122:125], v[234:237], v[14:17], v[122:125]
	s_waitcnt lgkmcnt(0)
; DEV unsigned pk2(float lo, float hi) { f32n2 v = {lo, hi}; bf16n2 b = __builtin_convertvector(v, bf16n2); return __builtin_bit_cast(unsigned, b); }
; #define LAS __attribute__((address_space(3)))
; template <int TT>
; DEV void mlstm_a_wave(LAS char* shm, const LAS char* kbuf, const bf16x8 (&qfr)[8], int fr, int fq, float m_prev, const LAS float* tpj, const LAS float* taj, f32x4 (&nacc)[3]) {
;     ...
;     s16x4 vlo[NK][3], vhi[NK][3];
; #pragma unroll
;     for (int kk = 0; kk < NK; ++kk)
; #pragma unroll
;         for (int vt = 0; vt < 3; ++vt) {
;             vlo[kk][vt] = __builtin_amdgcn_ds_read_tr16_b64_v4i16((LAS s16x4*)(shm + VT + (32 * kk + 4 * fq + (fr >> 2)) * VRS + (16 * vt + 4 * (fr & 3)) * 2));
;             vhi[kk][vt] = __builtin_amdgcn_ds_read_tr16_b64_v4i16((LAS s16x4*)(shm + VT + (32 * kk + 16 + 4 * fq + (fr >> 2)) * VRS + (16 * vt + 4 * (fr & 3)) * 2));
;         }
;     const int t = 16 * TT + fr;
;     const float btm = -fmaxf(m_prev, tpj[t]);
;     f32x4 sm[2 * NK];
; #pragma unroll
;     for (int jj = 0; jj < 2 * NK; ++jj) {
;         if (jj < NT) {
;             const f32x4 a4 = *(const LAS f32x4*)(taj + 16 * jj + 4 * fq);
; #pragma unroll
;             for (int r = 0; r < 4; ++r) {
;                 const int s_ = 16 * jj + 4 * fq + r;
;                 sm[jj][r] = (jj < TT || s_ <= t) ? sacc[jj < NT ? jj : 0][r] * __expf(btm + a4[r]) : 0.f;
;             }
;         } else sm[jj] = (f32x4){0.f, 0.f, 0.f, 0.f};
;     }
; #pragma unroll
;     for (int kk = 0; kk < NK; ++kk) {
;         const u32x4 u = (u32x4){pk2(sm[2 * kk][0], sm[2 * kk][1]), pk2(sm[2 * kk][2], sm[2 * kk][3]), pk2(sm[2 * kk + 1][0], sm[2 * kk + 1][1]), pk2(sm[2 * kk + 1][2], sm[2 * kk + 1][3])};
;         const bf16x8 af = *(const bf16x8*)&u;
; #pragma unroll
;         for (int vt = 0; vt < 3; ++vt) {
;             bf16x8 bv8; bv8[0] = vlo[kk][vt][0]; bv8[1] = vlo[kk][vt][1]; bv8[2] = vlo[kk][vt][2]; bv8[3] = vlo[kk][vt][3];
;             bv8[4] = vhi[kk][vt][0]; bv8[5] = vhi[kk][vt][1]; bv8[6] = vhi[kk][vt][2]; bv8[7] = vhi[kk][vt][3];
;             nacc[vt] = __builtin_amdgcn_mfma_f32_16x16x32_bf16(af, bv8, nacc[vt], 0, 0, 0);
	v_mfma_f32_16x16x32_bf16 v[130:133], v[130:133], v[18:21], v[126:129]
	v_mfma_f32_16x16x32_bf16 v[142:145], v[134:137], v[18:21], v[114:117]
	v_mfma_f32_16x16x32_bf16 v[146:149], v[138:141], v[18:21], v[118:121]
	v_mfma_f32_16x16x32_bf16 v[230:233], v[238:241], v[18:21], v[122:125]
	s_nop 0
	ds_read_b64_tr_b16 v[140:141], v0 offset:1536
	ds_read_b64_tr_b16 v[138:139], v0
	ds_read_b64_tr_b16 v[134:135], v0 offset:32
	ds_read_b64_tr_b16 v[136:137], v0 offset:1568
	ds_read_b64_tr_b16 v[126:127], v0 offset:64
	ds_read_b64_tr_b16 v[128:129], v0 offset:1600
	ds_read_b64_tr_b16 v[118:119], v0 offset:3072
	ds_read_b64_tr_b16 v[120:121], v0 offset:4608
	ds_read_b64_tr_b16 v[114:115], v0 offset:3104
	ds_read_b64_tr_b16 v[116:117], v0 offset:4640
	ds_read_b64_tr_b16 v[122:123], v0 offset:3136
	ds_read_b64_tr_b16 v[124:125], v0 offset:4672
	v_add_u32_e32 v0, s40, v203
	v_add_u32_e32 v0, 0x235c0, v0
	ds_read_b32 v0, v0
	s_waitcnt lgkmcnt(0)
	v_max_f32_e32 v0, v0, v0
	v_max_f32_e32 v229, v227, v0
	v_add_u32_e32 v0, s40, v202
	v_add_u32_e32 v1, 0x21500, v0
	ds_read_b128 v[150:153], v1
	v_add_u32_e32 v1, 0x21540, v0
	ds_read_b128 v[234:237], v1
	v_add_u32_e32 v1, 0x21580, v0
	v_add_u32_e32 v0, 0x215c0, v0
	ds_read_b128 v[238:241], v1
	ds_read_b128 v[242:245], v0
	s_waitcnt lgkmcnt(1)
	v_sub_f32_e32 v1, v239, v229
	s_waitcnt lgkmcnt(0)
	v_sub_f32_e32 v0, v242, v229
	v_mul_f32_e32 v0, 0x3fb8aa3b, v0
	v_exp_f32_e32 v0, v0
	v_mul_f32_e32 v1, 0x3fb8aa3b, v1
	v_exp_f32_e32 v1, v1
	v_mul_f32_e32 v0, v230, v0
	v_cndmask_b32_e64 v230, v0, 0, s[6:7]
	v_sub_f32_e32 v0, v243, v229
	v_mul_f32_e32 v0, 0x3fb8aa3b, v0
	v_exp_f32_e32 v0, v0
	s_nop 0
	v_mul_f32_e32 v0, v231, v0
	v_cndmask_b32_e64 v231, 0, v0, s[8:9]
	v_sub_f32_e32 v0, v244, v229
	v_mul_f32_e32 v0, 0x3fb8aa3b, v0
	v_exp_f32_e32 v0, v0
	s_nop 0
	v_mul_f32_e32 v0, v232, v0
	v_cndmask_b32_e64 v232, v0, 0, s[10:11]
	v_sub_f32_e32 v0, v245, v229
	v_mul_f32_e32 v0, 0x3fb8aa3b, v0
	v_exp_f32_e32 v0, v0
	s_nop 0
	v_mul_f32_e32 v0, v233, v0
	v_cndmask_b32_e64 v233, v0, 0, s[12:13]
	v_sub_f32_e32 v0, v238, v229
	v_mul_f32_e32 v0, 0x3fb8aa3b, v0
	v_exp_f32_e32 v0, v0
	s_nop 0
	v_pk_mul_f32 v[0:1], v[146:147], v[0:1]
	v_sub_f32_e32 v146, v240, v229
	v_sub_f32_e32 v147, v241, v229
	v_mul_f32_e32 v146, 0x3fb8aa3b, v146
	v_mul_f32_e32 v147, 0x3fb8aa3b, v147
	v_exp_f32_e32 v146, v146
	v_exp_f32_e32 v147, v147
	s_nop 0
	v_pk_mul_f32 v[146:147], v[148:149], v[146:147]
	v_sub_f32_e32 v148, v234, v229
	v_sub_f32_e32 v149, v235, v229
	v_mul_f32_e32 v148, 0x3fb8aa3b, v148
	v_mul_f32_e32 v149, 0x3fb8aa3b, v149
	v_exp_f32_e32 v148, v148
	v_exp_f32_e32 v149, v149
	s_nop 0
	v_pk_mul_f32 v[142:143], v[142:143], v[148:149]
	v_sub_f32_e32 v148, v236, v229
	v_sub_f32_e32 v149, v237, v229
	v_mul_f32_e32 v148, 0x3fb8aa3b, v148
	v_mul_f32_e32 v149, 0x3fb8aa3b, v149
	v_exp_f32_e32 v148, v148
	v_exp_f32_e32 v149, v149
	s_nop 0
	v_pk_mul_f32 v[144:145], v[144:145], v[148:149]
	v_sub_f32_e32 v148, v150, v229
	v_sub_f32_e32 v149, v151, v229
	v_mul_f32_e32 v148, 0x3fb8aa3b, v148
	v_mul_f32_e32 v149, 0x3fb8aa3b, v149
	v_exp_f32_e32 v148, v148
	v_exp_f32_e32 v149, v149
	s_nop 0
	v_pk_mul_f32 v[130:131], v[130:131], v[148:149]
	v_sub_f32_e32 v148, v152, v229
	v_sub_f32_e32 v149, v153, v229
	v_mul_f32_e32 v148, 0x3fb8aa3b, v148
	v_mul_f32_e32 v149, 0x3fb8aa3b, v149
	v_exp_f32_e32 v148, v148
	v_exp_f32_e32 v149, v149
	v_cvt_pk_bf16_f32 v130, v130, v131
	v_pk_mul_f32 v[132:133], v[132:133], v[148:149]
	s_nop 0
	v_cvt_pk_bf16_f32 v131, v132, v133
	v_cvt_pk_bf16_f32 v132, v142, v143
	v_cvt_pk_bf16_f32 v133, v144, v145
	s_nop 1
	v_mfma_f32_16x16x32_bf16 v[138:141], v[130:133], v[138:141], 0
	v_mfma_f32_16x16x32_bf16 v[134:137], v[130:133], v[134:137], 0
	v_mfma_f32_16x16x32_bf16 v[126:129], v[130:133], v[126:129], 0
	v_cvt_pk_bf16_f32 v130, v0, v1
	v_cvt_pk_bf16_f32 v131, v146, v147
	v_cvt_pk_bf16_f32 v132, v230, v231
	v_cvt_pk_bf16_f32 v133, v232, v233
	s_nop 1
	v_mfma_f32_16x16x32_bf16 v[118:121], v[130:133], v[118:121], v[138:141]
	v_mfma_f32_16x16x32_bf16 v[114:117], v[130:133], v[114:117], v[134:137]
	v_mfma_f32_16x16x32_bf16 v[122:125], v[130:133], v[122:125], v[126:129]

; #define LAS __attribute__((address_space(3)))
; template <int TT>
; DEV void mlstm_a_wave(LAS char* shm, const LAS char* kbuf, const bf16x8 (&qfr)[8], int fr, int fq, float m_prev, const LAS float* tpj, const LAS float* taj, f32x4 (&nacc)[3]) {
;     ...
;     for (int jj = 0; jj < NT; ++jj) kf[jj] = *(const LAS bf16x8*)MLK_ADDR(jj, 0);
; #pragma unroll
;     for (int ks = 0; ks < 8; ++ks) {
;         bf16x8 kn[NT];
; #pragma unroll
;         for (int jj = 0; jj < NT; ++jj) kn[jj] = kf[jj];
;         if (ks < 7) {
; #pragma unroll
;             for (int jj = 0; jj < NT; ++jj) kn[jj] = *(const LAS bf16x8*)MLK_ADDR(jj, ks + 1);
;         }
; #pragma unroll
;         for (int jj = 0; jj < NT; ++jj) sacc[jj] = __builtin_amdgcn_mfma_f32_16x16x32_bf16(kf[jj], qfr[ks], sacc[jj], 0, 0, 0);
; #pragma unroll
;         for (int jj = 0; jj < NT; ++jj) kf[jj] = kn[jj];
;     }
;     ...
;     constexpr int NK = (TT >= 2) ? 2 : 1;
;     s16x4 vlo[NK][3], vhi[NK][3];
; #pragma unroll
;     for (int kk = 0; kk < NK; ++kk)
; #pragma unroll
;         for (int vt = 0; vt < 3; ++vt) {
;             vlo[kk][vt] = __builtin_amdgcn_ds_read_tr16_b64_v4i16((LAS s16x4*)(shm + VT + (32 * kk + 4 * fq + (fr >> 2)) * VRS + (16 * vt + 4 * (fr & 3)) * 2));
;             vhi[kk][vt] = __builtin_amdgcn_ds_read_tr16_b64_v4i16((LAS s16x4*)(shm + VT + (32 * kk + 16 + 4 * fq + (fr >> 2)) * VRS + (16 * vt + 4 * (fr & 3)) * 2));
;         }
;     const int t = 16 * TT + fr;
;     const float btm = -fmaxf(m_prev, tpj[t]);
;     f32x4 sm[2 * NK];
; #pragma unroll
;     for (int jj = 0; jj < 2 * NK; ++jj) {
;         if (jj < NT) {
;             const f32x4 a4 = *(const LAS f32x4*)(taj + 16 * jj + 4 * fq);
; #pragma unroll
;             for (int r = 0; r < 4; ++r) {
;                 const int s_ = 16 * jj + 4 * fq + r;
;                 sm[jj][r] = (jj < TT || s_ <= t) ? sacc[jj < NT ? jj : 0][r] * __expf(btm + a4[r]) : 0.f;
;             }
;         } else sm[jj] = (f32x4){0.f, 0.f, 0.f, 0.f};
;     }
; #pragma unroll
;     for (int kk = 0; kk < NK; ++kk) {
;         const u32x4 u = (u32x4){pk2(sm[2 * kk][0], sm[2 * kk][1]), pk2(sm[2 * kk][2], sm[2 * kk][3]), pk2(sm[2 * kk + 1][0], sm[2 * kk + 1][1]), pk2(sm[2 * kk + 1][2], sm[2 * kk + 1][3])};
;         const bf16x8 af = *(const bf16x8*)&u;
; #pragma unroll
;         for (int vt = 0; vt < 3; ++vt) {
.LBB0_1510:
	s_andn2_b64 vcc, exec, s[0:1]
	s_cbranch_vccnz .LBB0_1515
	v_add_u32_e32 v131, v5, v183
	v_add_u32_e32 v130, v5, v184
	v_add_u32_e32 v129, v5, v185
	v_add_u32_e32 v5, s40, v202
	s_mov_b64 s[0:1], -1
	s_cmp_eq_u32 s61, 1
	v_add_u32_e32 v127, v187, v186
	v_add_u32_e32 v128, s40, v203
	v_add_u32_e32 v126, 0x21500, v5
	s_cbranch_scc1 .LBB0_1513
	ds_read_b128 v[114:117], v131
	ds_read_b128 v[122:125], v130
	s_waitcnt lgkmcnt(0)
	v_mfma_f32_16x16x32_bf16 v[118:121], v[110:113], v[38:41], 0
	v_add_u32_e32 v0, 0x23500, v128
	s_mov_b64 s[0:1], 0
	v_mfma_f32_16x16x32_bf16 v[114:117], v[114:117], v[34:37], v[118:121]
	s_nop 4
	ds_read_b128 v[118:121], v129
	v_mfma_f32_16x16x32_bf16 v[114:117], v[122:125], v[30:33], v[114:117]
	ds_read_b128 v[122:125], v4 offset:256
	s_waitcnt lgkmcnt(0)
	v_mfma_f32_16x16x32_bf16 v[114:117], v[118:121], v[10:13], v[114:117]
	ds_read_b128 v[118:121], v131 offset:256
	v_mfma_f32_16x16x32_bf16 v[114:117], v[122:125], v[26:29], v[114:117]
	ds_read_b128 v[122:125], v130 offset:256
	s_waitcnt lgkmcnt(0)
	v_mfma_f32_16x16x32_bf16 v[114:117], v[118:121], v[22:25], v[114:117]
	ds_read_b128 v[118:121], v129 offset:256
	v_mfma_f32_16x16x32_bf16 v[132:135], v[122:125], v[14:17], v[114:117]
	s_nop 0
	ds_read_b64_tr_b16 v[138:139], v127 offset:1536
	ds_read_b64_tr_b16 v[136:137], v127
	s_nop 2
	ds_read_b64_tr_b16 v[114:115], v127 offset:32
	ds_read_b64_tr_b16 v[116:117], v127 offset:1568
	ds_read_b64_tr_b16 v[122:123], v127 offset:64
	ds_read_b64_tr_b16 v[124:125], v127 offset:1600
	ds_read_b32 v0, v0
	s_waitcnt lgkmcnt(7)
	v_mfma_f32_16x16x32_bf16 v[118:121], v[118:121], v[18:21], v[132:135]
	s_nop 2
	ds_read_b128 v[132:135], v126
	s_waitcnt lgkmcnt(1)
	v_max_f32_e32 v0, v0, v0
	v_max_f32_e32 v0, v227, v0
	s_waitcnt lgkmcnt(0)
	v_sub_f32_e32 v1, v132, v0
	v_mul_f32_e32 v1, 0x3fb8aa3b, v1
	v_exp_f32_e32 v1, v1
	s_nop 0
	v_mul_f32_e32 v1, v118, v1
	v_sub_f32_e32 v118, v133, v0
	v_mul_f32_e32 v118, 0x3fb8aa3b, v118
	v_exp_f32_e32 v118, v118
	v_cndmask_b32_e64 v1, v1, 0, s[6:7]
	v_mul_f32_e32 v118, v119, v118
	v_sub_f32_e32 v119, v134, v0
	v_sub_f32_e32 v0, v135, v0
	v_mul_f32_e32 v119, 0x3fb8aa3b, v119
	v_mul_f32_e32 v0, 0x3fb8aa3b, v0
	v_exp_f32_e32 v119, v119
	v_exp_f32_e32 v0, v0
	v_cndmask_b32_e64 v118, 0, v118, s[8:9]
	v_cvt_pk_bf16_f32 v132, v1, v118
	v_mul_f32_e32 v119, v120, v119
	v_mul_f32_e32 v0, v121, v0
	v_cndmask_b32_e64 v119, v119, 0, s[10:11]
	v_cndmask_b32_e64 v0, v0, 0, s[12:13]
	v_cvt_pk_bf16_f32 v133, v119, v0
	v_mov_b32_e32 v134, v3
	v_mov_b32_e32 v135, v3
	s_nop 1
	v_mfma_f32_16x16x32_bf16 v[118:121], v[132:135], v[136:139], 0
	v_mfma_f32_16x16x32_bf16 v[114:117], v[132:135], v[114:117], 0
	v_mfma_f32_16x16x32_bf16 v[122:125], v[132:135], v[122:125], 0

; DEV unsigned xb_ld(unsigned* p) { return __hip_atomic_load(p, __ATOMIC_RELAXED, __HIP_MEMORY_SCOPE_AGENT); }
; #define XB_SPIN(cond, bar) do { unsigned _sp = 0; while (cond) { __builtin_amdgcn_s_sleep(1); \
;     if ((++_sp & 255u) == 0u) { if (xb_ld(&(bar)[XB_TMO])) break; if (_sp > XB_SPIN_CAP) { atomicAdd(&(bar)[XB_TMO], 1u); break; } } } } while (0)
; DEV void xcd_wait_lds(LAS char* lds) {
;     ...
;         if (mode != 3u) XB_SPIN(xb_ld(&bar[XB_TOPGEN]) <= val, bar);
.LBB0_1576:
	s_and_b32 s52, s31, 0xff
	s_mov_b64 s[66:67], -1
	s_cmp_lg_u32 s52, 0
	s_mov_b64 s[70:71], -1
	s_sleep 3
	s_cbranch_scc0 .LBB0_1579
	s_and_b64 vcc, exec, s[70:71]
	s_cbranch_vccz .LBB0_1575

.LBB0_1617:
	global_load_dword v0, v133, s[40:41] sc1
	s_mov_b64 s[42:43], -1
	s_mov_b64 s[54:55], -1
	s_waitcnt vmcnt(0)
	v_cmp_lt_u32_e32 vcc, 1, v0
	s_cbranch_vccnz .LBB0_1616
	s_sleep 3
	global_load_dword v0, v133, s[40:41] sc1
	s_waitcnt vmcnt(0)
	v_cmp_gt_u32_e32 vcc, 2, v0
	s_cbranch_vccz .LBB0_1616
	s_sleep 3
	global_load_dword v0, v133, s[40:41] sc1
	s_waitcnt vmcnt(0)
	v_cmp_gt_u32_e32 vcc, 2, v0
	s_cbranch_vccz .LBB0_1616
	s_sleep 3
	global_load_dword v0, v133, s[40:41] sc1
	s_waitcnt vmcnt(0)
	v_cmp_gt_u32_e32 vcc, 2, v0
	s_cbranch_vccz .LBB0_1616
	s_sleep 3
	global_load_dword v0, v133, s[40:41] sc1
	s_waitcnt vmcnt(0)
	v_cmp_gt_u32_e32 vcc, 2, v0
	s_cbranch_vccz .LBB0_1616
	s_add_i32 s31, s31, -5
	s_cmp_eq_u32 s31, 0
	s_mov_b64 s[42:43], 0
	s_cselect_b64 s[54:55], -1, 0
	s_sleep 3
	s_branch .LBB0_1616

; DEV unsigned xb_ld(unsigned* p) { return __hip_atomic_load(p, __ATOMIC_RELAXED, __HIP_MEMORY_SCOPE_AGENT); }
; DEV void xcd_barrier_complete(unsigned* bar, unsigned x, unsigned& nloc, unsigned& nx) {
;     const unsigned G = gridDim.x * gridDim.y * gridDim.z;
;     unsigned sum, cnt, mine, sp = 0u;
;     for (;;) {
;         sum = 0u; cnt = 0u; mine = 0u;
; #pragma nounroll
;         for (unsigned h = 0; h < 2; ++h) {
;             unsigned cv[8];
; #pragma unroll
;             for (unsigned j = 0; j < 8; ++j) cv[j] = xb_ld(&bar[XB_XCNT(8u * h + j)]);
; #pragma unroll
;             for (unsigned j = 0; j < 8; ++j) { sum += cv[j]; cnt += (cv[j] > 0u) ? 1u : 0u; if (8u * h + j == x) mine = cv[j]; }
;         }
;         if (sum == G) break;
;         __builtin_amdgcn_s_sleep(1);
;         if ((++sp & 255u) == 0u) { if (xb_ld(&bar[XB_TMO])) break; if (sp > XB_SPIN_CAP) { atomicAdd(&bar[XB_TMO], 1u); break; } }
;     }
;     nloc = mine > 0u ? mine : 1u; nx = cnt > 0u ? cnt : 1u;
; }
.LBB0_1642:
	s_lshl_b32 s12, s17, 9
	s_lshl_b64 s[0:1], s[12:13], 2
	s_add_u32 s0, s48, s0
	s_addc_u32 s1, s49, s1
	global_load_dword v0, v2, s[0:1] offset:1024 sc1
	global_load_dword v1, v2, s[0:1] offset:1280 sc1
	global_load_dword v6, v2, s[0:1] offset:1536 sc1
	global_load_dword v7, v2, s[0:1] offset:1792 sc1
	global_load_dword v8, v2, s[0:1] offset:2048 sc1
	global_load_dword v9, v2, s[0:1] offset:2304 sc1
	global_load_dword v10, v2, s[0:1] offset:2560 sc1
	global_load_dword v11, v2, s[0:1] offset:2816 sc1
	s_lshl_b32 s12, s17, 3
	s_cmp_eq_u32 s12, s33
	s_cselect_b64 vcc, -1, 0
	s_or_b32 s0, s12, 1
	s_cmp_eq_u32 s0, s33
	s_mov_b32 s17, 1
	s_waitcnt vmcnt(7)
	v_cmp_ne_u32_e64 s[0:1], 0, v0
	v_add_u32_e32 v5, v0, v5
	s_nop 0
	v_cndmask_b32_e64 v12, 0, 1, s[0:1]
	v_cndmask_b32_e32 v0, v4, v0, vcc
	s_waitcnt vmcnt(6)
	v_cmp_ne_u32_e32 vcc, 0, v1
	s_cselect_b64 s[0:1], -1, 0
	s_or_b32 s18, s12, 2
	s_waitcnt vmcnt(5)
	v_cmp_ne_u32_e64 s[4:5], 0, v6
	v_addc_co_u32_e32 v3, vcc, v3, v12, vcc
	s_cmp_eq_u32 s18, s33
	v_cndmask_b32_e64 v4, 0, 1, s[4:5]
	v_cndmask_b32_e64 v0, v0, v1, s[0:1]
	s_waitcnt vmcnt(4)
	v_cmp_ne_u32_e32 vcc, 0, v7
	s_cselect_b64 s[0:1], -1, 0
	s_waitcnt vmcnt(3)
	v_cmp_ne_u32_e64 s[4:5], 0, v8
	v_cndmask_b32_e64 v0, v0, v6, s[0:1]
	v_addc_co_u32_e32 v3, vcc, v3, v4, vcc
	s_or_b32 s0, s12, 3
	v_cndmask_b32_e64 v13, 0, 1, s[4:5]
	s_waitcnt vmcnt(2)
	v_cmp_ne_u32_e32 vcc, 0, v9
	s_cmp_eq_u32 s0, s33
	s_waitcnt vmcnt(1)
	v_cmp_ne_u32_e64 s[4:5], 0, v10
	v_addc_co_u32_e32 v3, vcc, v3, v13, vcc
	s_cselect_b64 s[0:1], -1, 0
	v_cndmask_b32_e64 v14, 0, 1, s[4:5]
	s_waitcnt vmcnt(0)
	v_cmp_ne_u32_e32 vcc, 0, v11
	v_cndmask_b32_e64 v0, v0, v7, s[0:1]
	s_or_b32 s0, s12, 4
	v_addc_co_u32_e32 v3, vcc, v3, v14, vcc
	s_cmp_eq_u32 s0, s33
	s_cselect_b64 vcc, -1, 0
	s_or_b32 s0, s12, 5
	v_add_u32_e32 v5, v5, v1
	s_cmp_eq_u32 s0, s33
	v_add_u32_e32 v1, v5, v6
	v_cndmask_b32_e32 v0, v0, v8, vcc
	s_cselect_b64 vcc, -1, 0
	s_or_b32 s0, s12, 6
	v_add_u32_e32 v1, v1, v7
	s_cmp_eq_u32 s0, s33
	v_add_u32_e32 v1, v1, v8
	v_cndmask_b32_e32 v0, v0, v9, vcc
	s_cselect_b64 vcc, -1, 0
	s_or_b32 s0, s12, 7
	v_add_u32_e32 v1, v1, v9
	s_cmp_eq_u32 s0, s33
	v_add_u32_e32 v1, v1, v10
	v_cndmask_b32_e32 v0, v0, v10, vcc
	s_cselect_b64 vcc, -1, 0
	v_add_u32_e32 v5, v1, v11
	v_cndmask_b32_e32 v4, v0, v11, vcc
	s_and_b64 vcc, exec, s[14:15]
	s_mov_b64 s[14:15], 0
	s_cbranch_vccnz .LBB0_1642
	v_cmp_eq_u32_e32 vcc, s2, v5
	s_mov_b64 s[0:1], -1
	s_mov_b64 s[4:5], -1
	s_cbranch_vccnz .LBB0_1640
	s_add_i32 s16, s16, 1
	s_and_b32 s4, s16, 0xff
	s_cmp_eq_u32 s4, 0
	s_cselect_b64 s[4:5], -1, 0
	s_and_b64 vcc, exec, s[4:5]
	s_sleep 3
	s_cbranch_vccz .LBB0_1640
	global_load_dword v0, v2, s[10:11] sc1
	s_waitcnt vmcnt(0)
	v_cmp_eq_u32_e32 vcc, 0, v0
	s_cbranch_vccz .LBB0_1640
	s_cmp_gt_u32 s16, 0x40000
	s_mov_b64 s[0:1], 0
	s_cselect_b64 s[4:5], -1, 0
	s_branch .LBB0_1640

; DEV unsigned xb_ld(unsigned* p) { return __hip_atomic_load(p, __ATOMIC_RELAXED, __HIP_MEMORY_SCOPE_AGENT); }
; #define XB_SPIN(cond, bar) do { unsigned _sp = 0; while (cond) { __builtin_amdgcn_s_sleep(1); \
;     if ((++_sp & 255u) == 0u) { if (xb_ld(&(bar)[XB_TMO])) break; if (_sp > XB_SPIN_CAP) { atomicAdd(&(bar)[XB_TMO], 1u); break; } } } } while (0)
; DEV void xcd_barrier1(const XcdBarrier& b) {
;     ...
;             else XB_SPIN(xb_ld(&bar[XB_TOPGEN]) <= tg, bar);
.LBB0_1658:
	s_and_b32 s22, s2, 0xff
	s_mov_b64 s[20:21], -1
	s_cmp_lg_u32 s22, 0
	s_mov_b64 s[24:25], -1
	s_sleep 3
	s_cbranch_scc1 .LBB0_1661
	global_load_dword v0, v2, s[12:13] sc1
	s_waitcnt vmcnt(0)
	v_cmp_eq_u32_e32 vcc, 0, v0
	s_cbranch_vccnz .LBB0_1663
	s_mov_b64 s[24:25], 0
	s_mov_b64 s[22:23], -1

; DEV unsigned xb_ld(unsigned* p) { return __hip_atomic_load(p, __ATOMIC_RELAXED, __HIP_MEMORY_SCOPE_AGENT); }
; #define XB_SPIN(cond, bar) do { unsigned _sp = 0; while (cond) { __builtin_amdgcn_s_sleep(1); \
;     if ((++_sp & 255u) == 0u) { if (xb_ld(&(bar)[XB_TMO])) break; if (_sp > XB_SPIN_CAP) { atomicAdd(&(bar)[XB_TMO], 1u); break; } } } } while (0)
; DEV void xcd_barrier1(const XcdBarrier& b) {
;     ...
;             XB_SPIN(xb_ld(&bar[XB_XGEN(b.x)]) <= gen, bar);
.LBB0_1675:
	s_and_b32 s20, s2, 0xff
	s_cmp_lg_u32 s20, 0
	s_mov_b64 s[22:23], -1
	s_sleep 3
	s_cbranch_scc1 .LBB0_1678
	global_load_dword v0, v2, s[12:13] sc1
	s_waitcnt vmcnt(0)
	v_cmp_eq_u32_e32 vcc, 0, v0
	s_cbranch_vccnz .LBB0_1680
	s_mov_b64 s[22:23], 0
	s_mov_b64 s[20:21], -1

.LBB0_1732:
	global_load_dword v136, v155, s[38:39] sc1
	s_mov_b64 s[40:41], -1
	s_mov_b64 s[42:43], -1
	s_waitcnt vmcnt(0)
	v_cmp_lt_u32_e32 vcc, 3, v136
	s_cbranch_vccnz .LBB0_1731
	s_sleep 3
	global_load_dword v136, v155, s[38:39] sc1
	s_waitcnt vmcnt(0)
	v_cmp_gt_u32_e32 vcc, 4, v136
	s_cbranch_vccz .LBB0_1731
	s_sleep 3
	global_load_dword v136, v155, s[38:39] sc1
	s_waitcnt vmcnt(0)
	v_cmp_gt_u32_e32 vcc, 4, v136
	s_cbranch_vccz .LBB0_1731
	s_sleep 3
	global_load_dword v136, v155, s[38:39] sc1
	s_waitcnt vmcnt(0)
	v_cmp_gt_u32_e32 vcc, 4, v136
	s_cbranch_vccz .LBB0_1731
	s_sleep 3
	global_load_dword v136, v155, s[38:39] sc1
	s_waitcnt vmcnt(0)
	v_cmp_gt_u32_e32 vcc, 4, v136
	s_cbranch_vccz .LBB0_1731
	s_add_i32 s18, s18, -5
	s_cmp_eq_u32 s18, 0
	s_mov_b64 s[40:41], 0
	s_cselect_b64 s[42:43], -1, 0
	s_sleep 3
	s_branch .LBB0_1731
